# fp8 table conversion: all 8 rows per wave/table loaded up front (32 loads in flight), second table streamed as first retires; fallback to row loop if grid != 512
# baseline (speedup 1.0000x reference)
; DI void fp8_rows(const float* __restrict__ src, unsigned char* __restrict__ dst, float* __restrict__ rs, int nrows) {
;   const int lane = threadIdx.x & 63, w = threadIdx.x >> 6;
;   for (int row = blockIdx.x * 4 + w; row < nrows; row += gridDim.x * 4) {
;     float4 v[4];
;     float am = 0.f;
; #pragma unroll
;     for (int i = 0; i < 4; ++i) {
;       v[i] = *(const float4*)(src + (size_t)row * 1024 + 4 * lane + 256 * i);
;       am = fmaxf(am, fmaxf(fmaxf(fabsf(v[i].x), fabsf(v[i].y)), fmaxf(fabsf(v[i].z), fabsf(v[i].w))));
;     }
;     am = fmaxf(am, __shfl_xor(am, 32)); am = fmaxf(am, __shfl_xor(am, 16)); am = fmaxf(am, __shfl_xor(am, 8));
;     am = fmaxf(am, __shfl_xor(am, 4)); am = fmaxf(am, __shfl_xor(am, 2)); am = fmaxf(am, __shfl_xor(am, 1));
.LBB0_404:
	s_and_b64 vcc, exec, s[12:13]
	s_mov_b64 s[12:13], -1
	s_cbranch_vccnz .LBB0_416
	s_and_saveexec_b64 s[6:7], s[8:9]
	s_xor_b64 s[12:13], exec, s[6:7]
	s_andn2_saveexec_b64 s[28:29], s[12:13]
	s_cbranch_execz .LBB0_415
	s_cmp_lg_u32 s26, 0x200
	s_cbranch_scc1 .Lmy_fp8o_0
	s_mov_b32 s98, 0x800000
	s_mov_b32 s99, 0
	s_mov_b32 s100, 0x200000
	s_mov_b32 s101, 0
	v_lshlrev_b32_e32 v16, 2, v226
	v_lshlrev_b32_e32 v10, 12, v226
	v_mov_b32_e32 v11, 0
	v_lshl_add_u64 v[10:11], v[166:167], 0, v[10:11]
	global_load_dwordx4 v[80:83], v[10:11], off
	global_load_dwordx4 v[84:87], v[10:11], off offset:1024
	global_load_dwordx4 v[88:91], v[10:11], off offset:2048
	global_load_dwordx4 v[92:95], v[10:11], off offset:3072
	v_lshl_add_u64 v[10:11], v[10:11], 0, s[98:99]
	global_load_dwordx4 v[96:99], v[10:11], off
	global_load_dwordx4 v[100:103], v[10:11], off offset:1024
	global_load_dwordx4 v[104:107], v[10:11], off offset:2048
	global_load_dwordx4 v[108:111], v[10:11], off offset:3072
	v_lshl_add_u64 v[10:11], v[10:11], 0, s[98:99]
	global_load_dwordx4 v[112:115], v[10:11], off
	global_load_dwordx4 v[116:119], v[10:11], off offset:1024
	global_load_dwordx4 v[120:123], v[10:11], off offset:2048
	global_load_dwordx4 v[124:127], v[10:11], off offset:3072
	v_lshl_add_u64 v[10:11], v[10:11], 0, s[98:99]
	global_load_dwordx4 v[128:131], v[10:11], off
	global_load_dwordx4 v[132:135], v[10:11], off offset:1024
	global_load_dwordx4 v[136:139], v[10:11], off offset:2048
	global_load_dwordx4 v[140:143], v[10:11], off offset:3072
	v_lshl_add_u64 v[10:11], v[10:11], 0, s[98:99]
	global_load_dwordx4 v[144:147], v[10:11], off
	global_load_dwordx4 v[148:151], v[10:11], off offset:1024
	global_load_dwordx4 v[152:155], v[10:11], off offset:2048
	global_load_dwordx4 v[156:159], v[10:11], off offset:3072
	v_lshl_add_u64 v[10:11], v[10:11], 0, s[98:99]
	global_load_dwordx4 v[172:175], v[10:11], off
	global_load_dwordx4 v[176:179], v[10:11], off offset:1024
	global_load_dwordx4 v[180:183], v[10:11], off offset:2048
	global_load_dwordx4 v[184:187], v[10:11], off offset:3072
	v_lshl_add_u64 v[10:11], v[10:11], 0, s[98:99]
	global_load_dwordx4 v[188:191], v[10:11], off
	global_load_dwordx4 v[192:195], v[10:11], off offset:1024
	global_load_dwordx4 v[196:199], v[10:11], off offset:2048
	global_load_dwordx4 v[200:203], v[10:11], off offset:3072
	v_lshl_add_u64 v[10:11], v[10:11], 0, s[98:99]
	global_load_dwordx4 v[204:207], v[10:11], off
	global_load_dwordx4 v[208:211], v[10:11], off offset:1024
	global_load_dwordx4 v[212:215], v[10:11], off offset:2048
	global_load_dwordx4 v[228:231], v[10:11], off offset:3072
	v_lshlrev_b32_e32 v14, 12, v226
	v_mov_b32_e32 v15, 0
	v_lshl_add_u64 v[14:15], v[168:169], 0, v[14:15]
	v_lshlrev_b32_e32 v12, 10, v226
	v_mov_b32_e32 v13, 0
	v_lshl_add_u64 v[12:13], v[162:163], 0, v[12:13]
	s_waitcnt vmcnt(28)
	v_max3_f32 v2, |v80|, |v81|, 0
	v_max3_f32 v2, |v82|, |v83|, v2
	v_max3_f32 v2, |v84|, |v85|, v2
	v_max3_f32 v2, |v86|, |v87|, v2
	v_max3_f32 v2, |v88|, |v89|, v2
	v_max3_f32 v2, |v90|, |v91|, v2
	v_max3_f32 v2, |v92|, |v93|, v2
	v_max3_f32 v2, |v94|, |v95|, v2
	s_nop 1
	v_max_f32_dpp v2, v2, v2 quad_perm:[1,0,3,2] row_mask:0xf bank_mask:0xf
	s_nop 1
	v_max_f32_dpp v2, v2, v2 quad_perm:[2,3,0,1] row_mask:0xf bank_mask:0xf
	s_nop 1
	v_max_f32_dpp v2, v2, v2 row_half_mirror row_mask:0xf bank_mask:0xf
	s_nop 1
	v_max_f32_dpp v2, v2, v2 row_mirror row_mask:0xf bank_mask:0xf
	v_mov_b32_e32 v17, v2
	s_nop 1
	v_permlane16_swap_b32_e32 v2, v17
	v_max_f32_e32 v2, v2, v17
	v_mov_b32_e32 v17, v2
	s_nop 1
	v_permlane32_swap_b32_e32 v2, v17
	v_max_f32_e32 v2, v2, v17
	s_waitcnt vmcnt(24)
	v_max3_f32 v3, |v96|, |v97|, 0
	v_max3_f32 v3, |v98|, |v99|, v3
	v_max3_f32 v3, |v100|, |v101|, v3
	v_max3_f32 v3, |v102|, |v103|, v3
	v_max3_f32 v3, |v104|, |v105|, v3
	v_max3_f32 v3, |v106|, |v107|, v3
	v_max3_f32 v3, |v108|, |v109|, v3
	v_max3_f32 v3, |v110|, |v111|, v3
	s_nop 1
	v_max_f32_dpp v3, v3, v3 quad_perm:[1,0,3,2] row_mask:0xf bank_mask:0xf
	s_nop 1
	v_max_f32_dpp v3, v3, v3 quad_perm:[2,3,0,1] row_mask:0xf bank_mask:0xf
	s_nop 1
	v_max_f32_dpp v3, v3, v3 row_half_mirror row_mask:0xf bank_mask:0xf
	s_nop 1
	v_max_f32_dpp v3, v3, v3 row_mirror row_mask:0xf bank_mask:0xf
	v_mov_b32_e32 v17, v3
	s_nop 1
	v_permlane16_swap_b32_e32 v3, v17
	v_max_f32_e32 v3, v3, v17
	v_mov_b32_e32 v17, v3
	s_nop 1
	v_permlane32_swap_b32_e32 v3, v17
	v_max_f32_e32 v3, v3, v17
	s_waitcnt vmcnt(20)
	v_max3_f32 v4, |v112|, |v113|, 0
	v_max3_f32 v4, |v114|, |v115|, v4
	v_max3_f32 v4, |v116|, |v117|, v4
	v_max3_f32 v4, |v118|, |v119|, v4
	v_max3_f32 v4, |v120|, |v121|, v4
	v_max3_f32 v4, |v122|, |v123|, v4
	v_max3_f32 v4, |v124|, |v125|, v4
	v_max3_f32 v4, |v126|, |v127|, v4
	s_nop 1
	v_max_f32_dpp v4, v4, v4 quad_perm:[1,0,3,2] row_mask:0xf bank_mask:0xf
	s_nop 1
	v_max_f32_dpp v4, v4, v4 quad_perm:[2,3,0,1] row_mask:0xf bank_mask:0xf
	s_nop 1
	v_max_f32_dpp v4, v4, v4 row_half_mirror row_mask:0xf bank_mask:0xf
	s_nop 1
	v_max_f32_dpp v4, v4, v4 row_mirror row_mask:0xf bank_mask:0xf
	v_mov_b32_e32 v17, v4
	s_nop 1
	v_permlane16_swap_b32_e32 v4, v17
	v_max_f32_e32 v4, v4, v17
	v_mov_b32_e32 v17, v4
	s_nop 1
	v_permlane32_swap_b32_e32 v4, v17
	v_max_f32_e32 v4, v4, v17
	s_waitcnt vmcnt(16)
; DI void fp8_rows(const float* __restrict__ src, unsigned char* __restrict__ dst, float* __restrict__ rs, int nrows) {
;     ...
;     for (int i = 0; i < 4; ++i) {
;       v[i] = *(const float4*)(src + (size_t)row * 1024 + 4 * lane + 256 * i);
;       am = fmaxf(am, fmaxf(fmaxf(fabsf(v[i].x), fabsf(v[i].y)), fmaxf(fabsf(v[i].z), fabsf(v[i].w))));
;     }
;     am = fmaxf(am, __shfl_xor(am, 32)); am = fmaxf(am, __shfl_xor(am, 16)); am = fmaxf(am, __shfl_xor(am, 8));
;     am = fmaxf(am, __shfl_xor(am, 4)); am = fmaxf(am, __shfl_xor(am, 2)); am = fmaxf(am, __shfl_xor(am, 1));
;     const float sc = am > 0.f ? 440.f / am : 1.f;
;     if (lane == 0) rs[row] = am > 0.f ? am / 440.f : 1.f;
; #pragma unroll
;     for (int i = 0; i < 4; ++i) {
;       int pk = __builtin_amdgcn_cvt_pk_fp8_f32(v[i].x * sc, v[i].y * sc, 0, false);
;       pk = __builtin_amdgcn_cvt_pk_fp8_f32(v[i].z * sc, v[i].w * sc, pk, true);
;       *(int*)(dst + (size_t)row * 1024 + 4 * lane + 256 * i) = pk;
	v_max3_f32 v5, |v128|, |v129|, 0
	v_max3_f32 v5, |v130|, |v131|, v5
	v_max3_f32 v5, |v132|, |v133|, v5
	v_max3_f32 v5, |v134|, |v135|, v5
	v_max3_f32 v5, |v136|, |v137|, v5
	v_max3_f32 v5, |v138|, |v139|, v5
	v_max3_f32 v5, |v140|, |v141|, v5
	v_max3_f32 v5, |v142|, |v143|, v5
	s_nop 1
	v_max_f32_dpp v5, v5, v5 quad_perm:[1,0,3,2] row_mask:0xf bank_mask:0xf
	s_nop 1
	v_max_f32_dpp v5, v5, v5 quad_perm:[2,3,0,1] row_mask:0xf bank_mask:0xf
	s_nop 1
	v_max_f32_dpp v5, v5, v5 row_half_mirror row_mask:0xf bank_mask:0xf
	s_nop 1
	v_max_f32_dpp v5, v5, v5 row_mirror row_mask:0xf bank_mask:0xf
	v_mov_b32_e32 v17, v5
	s_nop 1
	v_permlane16_swap_b32_e32 v5, v17
	v_max_f32_e32 v5, v5, v17
	v_mov_b32_e32 v17, v5
	s_nop 1
	v_permlane32_swap_b32_e32 v5, v17
	v_max_f32_e32 v5, v5, v17
	s_waitcnt vmcnt(12)
	v_max3_f32 v6, |v144|, |v145|, 0
	v_max3_f32 v6, |v146|, |v147|, v6
	v_max3_f32 v6, |v148|, |v149|, v6
	v_max3_f32 v6, |v150|, |v151|, v6
	v_max3_f32 v6, |v152|, |v153|, v6
	v_max3_f32 v6, |v154|, |v155|, v6
	v_max3_f32 v6, |v156|, |v157|, v6
	v_max3_f32 v6, |v158|, |v159|, v6
	s_nop 1
	v_max_f32_dpp v6, v6, v6 quad_perm:[1,0,3,2] row_mask:0xf bank_mask:0xf
	s_nop 1
	v_max_f32_dpp v6, v6, v6 quad_perm:[2,3,0,1] row_mask:0xf bank_mask:0xf
	s_nop 1
	v_max_f32_dpp v6, v6, v6 row_half_mirror row_mask:0xf bank_mask:0xf
	s_nop 1
	v_max_f32_dpp v6, v6, v6 row_mirror row_mask:0xf bank_mask:0xf
	v_mov_b32_e32 v17, v6
	s_nop 1
	v_permlane16_swap_b32_e32 v6, v17
	v_max_f32_e32 v6, v6, v17
	v_mov_b32_e32 v17, v6
	s_nop 1
	v_permlane32_swap_b32_e32 v6, v17
	v_max_f32_e32 v6, v6, v17
	s_waitcnt vmcnt(8)
	v_max3_f32 v7, |v172|, |v173|, 0
	v_max3_f32 v7, |v174|, |v175|, v7
	v_max3_f32 v7, |v176|, |v177|, v7
	v_max3_f32 v7, |v178|, |v179|, v7
	v_max3_f32 v7, |v180|, |v181|, v7
	v_max3_f32 v7, |v182|, |v183|, v7
	v_max3_f32 v7, |v184|, |v185|, v7
	v_max3_f32 v7, |v186|, |v187|, v7
	s_nop 1
	v_max_f32_dpp v7, v7, v7 quad_perm:[1,0,3,2] row_mask:0xf bank_mask:0xf
	s_nop 1
	v_max_f32_dpp v7, v7, v7 quad_perm:[2,3,0,1] row_mask:0xf bank_mask:0xf
	s_nop 1
	v_max_f32_dpp v7, v7, v7 row_half_mirror row_mask:0xf bank_mask:0xf
	s_nop 1
	v_max_f32_dpp v7, v7, v7 row_mirror row_mask:0xf bank_mask:0xf
	v_mov_b32_e32 v17, v7
	s_nop 1
	v_permlane16_swap_b32_e32 v7, v17
	v_max_f32_e32 v7, v7, v17
	v_mov_b32_e32 v17, v7
	s_nop 1
	v_permlane32_swap_b32_e32 v7, v17
	v_max_f32_e32 v7, v7, v17
	s_waitcnt vmcnt(4)
	v_max3_f32 v8, |v188|, |v189|, 0
	v_max3_f32 v8, |v190|, |v191|, v8
	v_max3_f32 v8, |v192|, |v193|, v8
	v_max3_f32 v8, |v194|, |v195|, v8
	v_max3_f32 v8, |v196|, |v197|, v8
	v_max3_f32 v8, |v198|, |v199|, v8
	v_max3_f32 v8, |v200|, |v201|, v8
	v_max3_f32 v8, |v202|, |v203|, v8
	s_nop 1
	v_max_f32_dpp v8, v8, v8 quad_perm:[1,0,3,2] row_mask:0xf bank_mask:0xf
	s_nop 1
	v_max_f32_dpp v8, v8, v8 quad_perm:[2,3,0,1] row_mask:0xf bank_mask:0xf
	s_nop 1
	v_max_f32_dpp v8, v8, v8 row_half_mirror row_mask:0xf bank_mask:0xf
	s_nop 1
	v_max_f32_dpp v8, v8, v8 row_mirror row_mask:0xf bank_mask:0xf
	v_mov_b32_e32 v17, v8
	s_nop 1
	v_permlane16_swap_b32_e32 v8, v17
	v_max_f32_e32 v8, v8, v17
	v_mov_b32_e32 v17, v8
	s_nop 1
	v_permlane32_swap_b32_e32 v8, v17
	v_max_f32_e32 v8, v8, v17
	s_waitcnt vmcnt(0)
	v_max3_f32 v9, |v204|, |v205|, 0
	v_max3_f32 v9, |v206|, |v207|, v9
	v_max3_f32 v9, |v208|, |v209|, v9
	v_max3_f32 v9, |v210|, |v211|, v9
	v_max3_f32 v9, |v212|, |v213|, v9
	v_max3_f32 v9, |v214|, |v215|, v9
	v_max3_f32 v9, |v228|, |v229|, v9
	v_max3_f32 v9, |v230|, |v231|, v9
	s_nop 1
	v_max_f32_dpp v9, v9, v9 quad_perm:[1,0,3,2] row_mask:0xf bank_mask:0xf
	s_nop 1
	v_max_f32_dpp v9, v9, v9 quad_perm:[2,3,0,1] row_mask:0xf bank_mask:0xf
	s_nop 1
	v_max_f32_dpp v9, v9, v9 row_half_mirror row_mask:0xf bank_mask:0xf
	s_nop 1
	v_max_f32_dpp v9, v9, v9 row_mirror row_mask:0xf bank_mask:0xf
	v_mov_b32_e32 v17, v9
	s_nop 1
	v_permlane16_swap_b32_e32 v9, v17
	v_max_f32_e32 v9, v9, v17
	v_mov_b32_e32 v17, v9
	s_nop 1
	v_permlane32_swap_b32_e32 v9, v17
	v_max_f32_e32 v9, v9, v17
	v_cmp_lt_f32_e64 s[12:13], 0, v2
	v_div_scale_f32 v25, s[6:7], s5, s5, v2
	v_rcp_f32_e32 v26, v25
	v_div_scale_f32 v27, vcc, v2, s5, v2
	v_fma_f32 v28, -v25, v26, 1.0
	v_fmac_f32_e32 v26, v28, v26
	v_mul_f32_e32 v28, v27, v26
	v_fma_f32 v29, -v25, v28, v27
	v_fmac_f32_e32 v28, v29, v26
	v_fma_f32 v25, -v25, v28, v27
	v_div_fmas_f32 v25, v25, v26, v28
	v_div_fixup_f32 v30, v25, s5, v2
	v_cndmask_b32_e64 v30, 1.0, v30, s[12:13]
	v_mov_b32_e32 v17, v16
	s_and_saveexec_b64 s[54:55], s[10:11]
	global_store_dword v17, v30, s[34:35]
	s_or_b64 exec, exec, s[54:55]
	v_div_scale_f32 v25, s[6:7], v2, v2, s5
	v_rcp_f32_e32 v26, v25
	v_div_scale_f32 v27, vcc, s5, v2, s5
	v_fma_f32 v28, -v25, v26, 1.0
	v_fmac_f32_e32 v26, v28, v26
	v_mul_f32_e32 v28, v27, v26
	v_fma_f32 v29, -v25, v28, v27
	v_fmac_f32_e32 v28, v29, v26
	v_fma_f32 v25, -v25, v28, v27
	v_div_fmas_f32 v25, v25, v26, v28
	v_div_fixup_f32 v31, v25, v2, s5
	v_cndmask_b32_e64 v31, 1.0, v31, s[12:13]
	v_mul_f32_e32 v80, v80, v31
	v_mul_f32_e32 v81, v81, v31
	v_mul_f32_e32 v82, v82, v31
	v_mul_f32_e32 v83, v83, v31
	v_mul_f32_e32 v84, v84, v31
	v_mul_f32_e32 v85, v85, v31
	v_mul_f32_e32 v86, v86, v31
	v_mul_f32_e32 v87, v87, v31
	v_mul_f32_e32 v88, v88, v31
	v_mul_f32_e32 v89, v89, v31
	v_mul_f32_e32 v90, v90, v31
	v_mul_f32_e32 v91, v91, v31
	v_mul_f32_e32 v92, v92, v31
	v_mul_f32_e32 v93, v93, v31
	v_mul_f32_e32 v94, v94, v31
	v_mul_f32_e32 v95, v95, v31
	v_cvt_pk_fp8_f32 v80, v80, v81
	v_cvt_pk_fp8_f32 v84, v84, v85
	v_cvt_pk_fp8_f32 v88, v88, v89
	v_cvt_pk_fp8_f32 v92, v92, v93
	v_cvt_pk_fp8_f32 v80, v82, v83 op_sel:[0,0,1]
	v_cvt_pk_fp8_f32 v84, v86, v87 op_sel:[0,0,1]
; DI void fp8_rows(const float* __restrict__ src, unsigned char* __restrict__ dst, float* __restrict__ rs, int nrows) {
;     ...
;     const float sc = am > 0.f ? 440.f / am : 1.f;
;     if (lane == 0) rs[row] = am > 0.f ? am / 440.f : 1.f;
; #pragma unroll
;     for (int i = 0; i < 4; ++i) {
;       int pk = __builtin_amdgcn_cvt_pk_fp8_f32(v[i].x * sc, v[i].y * sc, 0, false);
;       pk = __builtin_amdgcn_cvt_pk_fp8_f32(v[i].z * sc, v[i].w * sc, pk, true);
;       *(int*)(dst + (size_t)row * 1024 + 4 * lane + 256 * i) = pk;
;     }
	v_cvt_pk_fp8_f32 v88, v90, v91 op_sel:[0,0,1]
	v_cvt_pk_fp8_f32 v92, v94, v95 op_sel:[0,0,1]
	global_store_dword v[12:13], v80, off
	global_store_dword v[12:13], v84, off offset:256
	global_store_dword v[12:13], v88, off offset:512
	global_store_dword v[12:13], v92, off offset:768
	v_lshl_add_u64 v[12:13], v[12:13], 0, s[100:101]
	global_load_dwordx4 v[80:83], v[14:15], off
	global_load_dwordx4 v[84:87], v[14:15], off offset:1024
	global_load_dwordx4 v[88:91], v[14:15], off offset:2048
	global_load_dwordx4 v[92:95], v[14:15], off offset:3072
	v_lshl_add_u64 v[14:15], v[14:15], 0, s[98:99]
	v_cmp_lt_f32_e64 s[12:13], 0, v3
	v_div_scale_f32 v25, s[6:7], s5, s5, v3
	v_rcp_f32_e32 v26, v25
	v_div_scale_f32 v27, vcc, v3, s5, v3
	v_fma_f32 v28, -v25, v26, 1.0
	v_fmac_f32_e32 v26, v28, v26
	v_mul_f32_e32 v28, v27, v26
	v_fma_f32 v29, -v25, v28, v27
	v_fmac_f32_e32 v28, v29, v26
	v_fma_f32 v25, -v25, v28, v27
	v_div_fmas_f32 v25, v25, v26, v28
	v_div_fixup_f32 v30, v25, s5, v3
	v_cndmask_b32_e64 v30, 1.0, v30, s[12:13]
	v_add_u32_e32 v17, 0x2000, v16
	s_and_saveexec_b64 s[54:55], s[10:11]
	global_store_dword v17, v30, s[34:35]
	s_or_b64 exec, exec, s[54:55]
	v_div_scale_f32 v25, s[6:7], v3, v3, s5
	v_rcp_f32_e32 v26, v25
	v_div_scale_f32 v27, vcc, s5, v3, s5
	v_fma_f32 v28, -v25, v26, 1.0
	v_fmac_f32_e32 v26, v28, v26
	v_mul_f32_e32 v28, v27, v26
	v_fma_f32 v29, -v25, v28, v27
	v_fmac_f32_e32 v28, v29, v26
	v_fma_f32 v25, -v25, v28, v27
	v_div_fmas_f32 v25, v25, v26, v28
	v_div_fixup_f32 v31, v25, v3, s5
	v_cndmask_b32_e64 v31, 1.0, v31, s[12:13]
	v_mul_f32_e32 v96, v96, v31
	v_mul_f32_e32 v97, v97, v31
	v_mul_f32_e32 v98, v98, v31
	v_mul_f32_e32 v99, v99, v31
	v_mul_f32_e32 v100, v100, v31
	v_mul_f32_e32 v101, v101, v31
	v_mul_f32_e32 v102, v102, v31
	v_mul_f32_e32 v103, v103, v31
	v_mul_f32_e32 v104, v104, v31
	v_mul_f32_e32 v105, v105, v31
	v_mul_f32_e32 v106, v106, v31
	v_mul_f32_e32 v107, v107, v31
	v_mul_f32_e32 v108, v108, v31
	v_mul_f32_e32 v109, v109, v31
	v_mul_f32_e32 v110, v110, v31
	v_mul_f32_e32 v111, v111, v31
	v_cvt_pk_fp8_f32 v96, v96, v97
	v_cvt_pk_fp8_f32 v100, v100, v101
	v_cvt_pk_fp8_f32 v104, v104, v105
	v_cvt_pk_fp8_f32 v108, v108, v109
	v_cvt_pk_fp8_f32 v96, v98, v99 op_sel:[0,0,1]
	v_cvt_pk_fp8_f32 v100, v102, v103 op_sel:[0,0,1]
	v_cvt_pk_fp8_f32 v104, v106, v107 op_sel:[0,0,1]
	v_cvt_pk_fp8_f32 v108, v110, v111 op_sel:[0,0,1]
	global_store_dword v[12:13], v96, off
	global_store_dword v[12:13], v100, off offset:256
	global_store_dword v[12:13], v104, off offset:512
	global_store_dword v[12:13], v108, off offset:768
	v_lshl_add_u64 v[12:13], v[12:13], 0, s[100:101]
	global_load_dwordx4 v[96:99], v[14:15], off
	global_load_dwordx4 v[100:103], v[14:15], off offset:1024
	global_load_dwordx4 v[104:107], v[14:15], off offset:2048
	global_load_dwordx4 v[108:111], v[14:15], off offset:3072
	v_lshl_add_u64 v[14:15], v[14:15], 0, s[98:99]
	v_cmp_lt_f32_e64 s[12:13], 0, v4
	v_div_scale_f32 v25, s[6:7], s5, s5, v4
	v_rcp_f32_e32 v26, v25
	v_div_scale_f32 v27, vcc, v4, s5, v4
	v_fma_f32 v28, -v25, v26, 1.0
	v_fmac_f32_e32 v26, v28, v26
	v_mul_f32_e32 v28, v27, v26
	v_fma_f32 v29, -v25, v28, v27
	v_fmac_f32_e32 v28, v29, v26
	v_fma_f32 v25, -v25, v28, v27
	v_div_fmas_f32 v25, v25, v26, v28
	v_div_fixup_f32 v30, v25, s5, v4
	v_cndmask_b32_e64 v30, 1.0, v30, s[12:13]
	v_add_u32_e32 v17, 0x4000, v16
	s_and_saveexec_b64 s[54:55], s[10:11]
	global_store_dword v17, v30, s[34:35]
	s_or_b64 exec, exec, s[54:55]
	v_div_scale_f32 v25, s[6:7], v4, v4, s5
	v_rcp_f32_e32 v26, v25
	v_div_scale_f32 v27, vcc, s5, v4, s5
	v_fma_f32 v28, -v25, v26, 1.0
	v_fmac_f32_e32 v26, v28, v26
	v_mul_f32_e32 v28, v27, v26
	v_fma_f32 v29, -v25, v28, v27
	v_fmac_f32_e32 v28, v29, v26
	v_fma_f32 v25, -v25, v28, v27
	v_div_fmas_f32 v25, v25, v26, v28
	v_div_fixup_f32 v31, v25, v4, s5
	v_cndmask_b32_e64 v31, 1.0, v31, s[12:13]
	v_mul_f32_e32 v112, v112, v31
	v_mul_f32_e32 v113, v113, v31
	v_mul_f32_e32 v114, v114, v31
	v_mul_f32_e32 v115, v115, v31
	v_mul_f32_e32 v116, v116, v31
	v_mul_f32_e32 v117, v117, v31
	v_mul_f32_e32 v118, v118, v31
	v_mul_f32_e32 v119, v119, v31
	v_mul_f32_e32 v120, v120, v31
	v_mul_f32_e32 v121, v121, v31
	v_mul_f32_e32 v122, v122, v31
	v_mul_f32_e32 v123, v123, v31
	v_mul_f32_e32 v124, v124, v31
	v_mul_f32_e32 v125, v125, v31
	v_mul_f32_e32 v126, v126, v31
	v_mul_f32_e32 v127, v127, v31
	v_cvt_pk_fp8_f32 v112, v112, v113
	v_cvt_pk_fp8_f32 v116, v116, v117
	v_cvt_pk_fp8_f32 v120, v120, v121
	v_cvt_pk_fp8_f32 v124, v124, v125
	v_cvt_pk_fp8_f32 v112, v114, v115 op_sel:[0,0,1]
	v_cvt_pk_fp8_f32 v116, v118, v119 op_sel:[0,0,1]
	v_cvt_pk_fp8_f32 v120, v122, v123 op_sel:[0,0,1]
	v_cvt_pk_fp8_f32 v124, v126, v127 op_sel:[0,0,1]
	global_store_dword v[12:13], v112, off
	global_store_dword v[12:13], v116, off offset:256
	global_store_dword v[12:13], v120, off offset:512
	global_store_dword v[12:13], v124, off offset:768
	v_lshl_add_u64 v[12:13], v[12:13], 0, s[100:101]
	global_load_dwordx4 v[112:115], v[14:15], off
	global_load_dwordx4 v[116:119], v[14:15], off offset:1024
	global_load_dwordx4 v[120:123], v[14:15], off offset:2048
	global_load_dwordx4 v[124:127], v[14:15], off offset:3072
	v_lshl_add_u64 v[14:15], v[14:15], 0, s[98:99]
	v_cmp_lt_f32_e64 s[12:13], 0, v5
	v_div_scale_f32 v25, s[6:7], s5, s5, v5
	v_rcp_f32_e32 v26, v25
	v_div_scale_f32 v27, vcc, v5, s5, v5
	v_fma_f32 v28, -v25, v26, 1.0
	v_fmac_f32_e32 v26, v28, v26
	v_mul_f32_e32 v28, v27, v26
	v_fma_f32 v29, -v25, v28, v27
	v_fmac_f32_e32 v28, v29, v26
	v_fma_f32 v25, -v25, v28, v27
	v_div_fmas_f32 v25, v25, v26, v28
	v_div_fixup_f32 v30, v25, s5, v5
	v_cndmask_b32_e64 v30, 1.0, v30, s[12:13]
; DI void fp8_rows(const float* __restrict__ src, unsigned char* __restrict__ dst, float* __restrict__ rs, int nrows) {
;     ...
;     const float sc = am > 0.f ? 440.f / am : 1.f;
;     if (lane == 0) rs[row] = am > 0.f ? am / 440.f : 1.f;
; #pragma unroll
;     for (int i = 0; i < 4; ++i) {
;       int pk = __builtin_amdgcn_cvt_pk_fp8_f32(v[i].x * sc, v[i].y * sc, 0, false);
;       pk = __builtin_amdgcn_cvt_pk_fp8_f32(v[i].z * sc, v[i].w * sc, pk, true);
;       *(int*)(dst + (size_t)row * 1024 + 4 * lane + 256 * i) = pk;
;     }
	v_add_u32_e32 v17, 0x6000, v16
	s_and_saveexec_b64 s[54:55], s[10:11]
	global_store_dword v17, v30, s[34:35]
	s_or_b64 exec, exec, s[54:55]
	v_div_scale_f32 v25, s[6:7], v5, v5, s5
	v_rcp_f32_e32 v26, v25
	v_div_scale_f32 v27, vcc, s5, v5, s5
	v_fma_f32 v28, -v25, v26, 1.0
	v_fmac_f32_e32 v26, v28, v26
	v_mul_f32_e32 v28, v27, v26
	v_fma_f32 v29, -v25, v28, v27
	v_fmac_f32_e32 v28, v29, v26
	v_fma_f32 v25, -v25, v28, v27
	v_div_fmas_f32 v25, v25, v26, v28
	v_div_fixup_f32 v31, v25, v5, s5
	v_cndmask_b32_e64 v31, 1.0, v31, s[12:13]
	v_mul_f32_e32 v128, v128, v31
	v_mul_f32_e32 v129, v129, v31
	v_mul_f32_e32 v130, v130, v31
	v_mul_f32_e32 v131, v131, v31
	v_mul_f32_e32 v132, v132, v31
	v_mul_f32_e32 v133, v133, v31
	v_mul_f32_e32 v134, v134, v31
	v_mul_f32_e32 v135, v135, v31
	v_mul_f32_e32 v136, v136, v31
	v_mul_f32_e32 v137, v137, v31
	v_mul_f32_e32 v138, v138, v31
	v_mul_f32_e32 v139, v139, v31
	v_mul_f32_e32 v140, v140, v31
	v_mul_f32_e32 v141, v141, v31
	v_mul_f32_e32 v142, v142, v31
	v_mul_f32_e32 v143, v143, v31
	v_cvt_pk_fp8_f32 v128, v128, v129
	v_cvt_pk_fp8_f32 v132, v132, v133
	v_cvt_pk_fp8_f32 v136, v136, v137
	v_cvt_pk_fp8_f32 v140, v140, v141
	v_cvt_pk_fp8_f32 v128, v130, v131 op_sel:[0,0,1]
	v_cvt_pk_fp8_f32 v132, v134, v135 op_sel:[0,0,1]
	v_cvt_pk_fp8_f32 v136, v138, v139 op_sel:[0,0,1]
	v_cvt_pk_fp8_f32 v140, v142, v143 op_sel:[0,0,1]
	global_store_dword v[12:13], v128, off
	global_store_dword v[12:13], v132, off offset:256
	global_store_dword v[12:13], v136, off offset:512
	global_store_dword v[12:13], v140, off offset:768
	v_lshl_add_u64 v[12:13], v[12:13], 0, s[100:101]
	global_load_dwordx4 v[128:131], v[14:15], off
	global_load_dwordx4 v[132:135], v[14:15], off offset:1024
	global_load_dwordx4 v[136:139], v[14:15], off offset:2048
	global_load_dwordx4 v[140:143], v[14:15], off offset:3072
	v_lshl_add_u64 v[14:15], v[14:15], 0, s[98:99]
	v_cmp_lt_f32_e64 s[12:13], 0, v6
	v_div_scale_f32 v25, s[6:7], s5, s5, v6
	v_rcp_f32_e32 v26, v25
	v_div_scale_f32 v27, vcc, v6, s5, v6
	v_fma_f32 v28, -v25, v26, 1.0
	v_fmac_f32_e32 v26, v28, v26
	v_mul_f32_e32 v28, v27, v26
	v_fma_f32 v29, -v25, v28, v27
	v_fmac_f32_e32 v28, v29, v26
	v_fma_f32 v25, -v25, v28, v27
	v_div_fmas_f32 v25, v25, v26, v28
	v_div_fixup_f32 v30, v25, s5, v6
	v_cndmask_b32_e64 v30, 1.0, v30, s[12:13]
	v_add_u32_e32 v17, 0x8000, v16
	s_and_saveexec_b64 s[54:55], s[10:11]
	global_store_dword v17, v30, s[34:35]
	s_or_b64 exec, exec, s[54:55]
	v_div_scale_f32 v25, s[6:7], v6, v6, s5
	v_rcp_f32_e32 v26, v25
	v_div_scale_f32 v27, vcc, s5, v6, s5
	v_fma_f32 v28, -v25, v26, 1.0
	v_fmac_f32_e32 v26, v28, v26
	v_mul_f32_e32 v28, v27, v26
	v_fma_f32 v29, -v25, v28, v27
	v_fmac_f32_e32 v28, v29, v26
	v_fma_f32 v25, -v25, v28, v27
	v_div_fmas_f32 v25, v25, v26, v28
	v_div_fixup_f32 v31, v25, v6, s5
	v_cndmask_b32_e64 v31, 1.0, v31, s[12:13]
	v_mul_f32_e32 v144, v144, v31
	v_mul_f32_e32 v145, v145, v31
	v_mul_f32_e32 v146, v146, v31
	v_mul_f32_e32 v147, v147, v31
	v_mul_f32_e32 v148, v148, v31
	v_mul_f32_e32 v149, v149, v31
	v_mul_f32_e32 v150, v150, v31
	v_mul_f32_e32 v151, v151, v31
	v_mul_f32_e32 v152, v152, v31
	v_mul_f32_e32 v153, v153, v31
	v_mul_f32_e32 v154, v154, v31
	v_mul_f32_e32 v155, v155, v31
	v_mul_f32_e32 v156, v156, v31
	v_mul_f32_e32 v157, v157, v31
	v_mul_f32_e32 v158, v158, v31
	v_mul_f32_e32 v159, v159, v31
	v_cvt_pk_fp8_f32 v144, v144, v145
	v_cvt_pk_fp8_f32 v148, v148, v149
	v_cvt_pk_fp8_f32 v152, v152, v153
	v_cvt_pk_fp8_f32 v156, v156, v157
	v_cvt_pk_fp8_f32 v144, v146, v147 op_sel:[0,0,1]
	v_cvt_pk_fp8_f32 v148, v150, v151 op_sel:[0,0,1]
	v_cvt_pk_fp8_f32 v152, v154, v155 op_sel:[0,0,1]
	v_cvt_pk_fp8_f32 v156, v158, v159 op_sel:[0,0,1]
	global_store_dword v[12:13], v144, off
	global_store_dword v[12:13], v148, off offset:256
	global_store_dword v[12:13], v152, off offset:512
	global_store_dword v[12:13], v156, off offset:768
	v_lshl_add_u64 v[12:13], v[12:13], 0, s[100:101]
	global_load_dwordx4 v[144:147], v[14:15], off
	global_load_dwordx4 v[148:151], v[14:15], off offset:1024
	global_load_dwordx4 v[152:155], v[14:15], off offset:2048
	global_load_dwordx4 v[156:159], v[14:15], off offset:3072
	v_lshl_add_u64 v[14:15], v[14:15], 0, s[98:99]
	v_cmp_lt_f32_e64 s[12:13], 0, v7
	v_div_scale_f32 v25, s[6:7], s5, s5, v7
	v_rcp_f32_e32 v26, v25
	v_div_scale_f32 v27, vcc, v7, s5, v7
	v_fma_f32 v28, -v25, v26, 1.0
	v_fmac_f32_e32 v26, v28, v26
	v_mul_f32_e32 v28, v27, v26
	v_fma_f32 v29, -v25, v28, v27
	v_fmac_f32_e32 v28, v29, v26
	v_fma_f32 v25, -v25, v28, v27
	v_div_fmas_f32 v25, v25, v26, v28
	v_div_fixup_f32 v30, v25, s5, v7
	v_cndmask_b32_e64 v30, 1.0, v30, s[12:13]
	v_add_u32_e32 v17, 0xa000, v16
	s_and_saveexec_b64 s[54:55], s[10:11]
	global_store_dword v17, v30, s[34:35]
	s_or_b64 exec, exec, s[54:55]
	v_div_scale_f32 v25, s[6:7], v7, v7, s5
	v_rcp_f32_e32 v26, v25
	v_div_scale_f32 v27, vcc, s5, v7, s5
	v_fma_f32 v28, -v25, v26, 1.0
	v_fmac_f32_e32 v26, v28, v26
	v_mul_f32_e32 v28, v27, v26
	v_fma_f32 v29, -v25, v28, v27
	v_fmac_f32_e32 v28, v29, v26
	v_fma_f32 v25, -v25, v28, v27
	v_div_fmas_f32 v25, v25, v26, v28
	v_div_fixup_f32 v31, v25, v7, s5
	v_cndmask_b32_e64 v31, 1.0, v31, s[12:13]
	v_mul_f32_e32 v172, v172, v31
	v_mul_f32_e32 v173, v173, v31
	v_mul_f32_e32 v174, v174, v31
	v_mul_f32_e32 v175, v175, v31
	v_mul_f32_e32 v176, v176, v31
	v_mul_f32_e32 v177, v177, v31
	v_mul_f32_e32 v178, v178, v31
	v_mul_f32_e32 v179, v179, v31
	v_mul_f32_e32 v180, v180, v31
	v_mul_f32_e32 v181, v181, v31
	v_mul_f32_e32 v182, v182, v31
	v_mul_f32_e32 v183, v183, v31
	v_mul_f32_e32 v184, v184, v31
	v_mul_f32_e32 v185, v185, v31
	v_mul_f32_e32 v186, v186, v31
; DI void fp8_rows(const float* __restrict__ src, unsigned char* __restrict__ dst, float* __restrict__ rs, int nrows) {
;     ...
;     const float sc = am > 0.f ? 440.f / am : 1.f;
;     if (lane == 0) rs[row] = am > 0.f ? am / 440.f : 1.f;
; #pragma unroll
;     for (int i = 0; i < 4; ++i) {
;       int pk = __builtin_amdgcn_cvt_pk_fp8_f32(v[i].x * sc, v[i].y * sc, 0, false);
;       pk = __builtin_amdgcn_cvt_pk_fp8_f32(v[i].z * sc, v[i].w * sc, pk, true);
;       *(int*)(dst + (size_t)row * 1024 + 4 * lane + 256 * i) = pk;
;     }
	v_mul_f32_e32 v187, v187, v31
	v_cvt_pk_fp8_f32 v172, v172, v173
	v_cvt_pk_fp8_f32 v176, v176, v177
	v_cvt_pk_fp8_f32 v180, v180, v181
	v_cvt_pk_fp8_f32 v184, v184, v185
	v_cvt_pk_fp8_f32 v172, v174, v175 op_sel:[0,0,1]
	v_cvt_pk_fp8_f32 v176, v178, v179 op_sel:[0,0,1]
	v_cvt_pk_fp8_f32 v180, v182, v183 op_sel:[0,0,1]
	v_cvt_pk_fp8_f32 v184, v186, v187 op_sel:[0,0,1]
	global_store_dword v[12:13], v172, off
	global_store_dword v[12:13], v176, off offset:256
	global_store_dword v[12:13], v180, off offset:512
	global_store_dword v[12:13], v184, off offset:768
	v_lshl_add_u64 v[12:13], v[12:13], 0, s[100:101]
	global_load_dwordx4 v[172:175], v[14:15], off
	global_load_dwordx4 v[176:179], v[14:15], off offset:1024
	global_load_dwordx4 v[180:183], v[14:15], off offset:2048
	global_load_dwordx4 v[184:187], v[14:15], off offset:3072
	v_lshl_add_u64 v[14:15], v[14:15], 0, s[98:99]
	v_cmp_lt_f32_e64 s[12:13], 0, v8
	v_div_scale_f32 v25, s[6:7], s5, s5, v8
	v_rcp_f32_e32 v26, v25
	v_div_scale_f32 v27, vcc, v8, s5, v8
	v_fma_f32 v28, -v25, v26, 1.0
	v_fmac_f32_e32 v26, v28, v26
	v_mul_f32_e32 v28, v27, v26
	v_fma_f32 v29, -v25, v28, v27
	v_fmac_f32_e32 v28, v29, v26
	v_fma_f32 v25, -v25, v28, v27
	v_div_fmas_f32 v25, v25, v26, v28
	v_div_fixup_f32 v30, v25, s5, v8
	v_cndmask_b32_e64 v30, 1.0, v30, s[12:13]
	v_add_u32_e32 v17, 0xc000, v16
	s_and_saveexec_b64 s[54:55], s[10:11]
	global_store_dword v17, v30, s[34:35]
	s_or_b64 exec, exec, s[54:55]
	v_div_scale_f32 v25, s[6:7], v8, v8, s5
	v_rcp_f32_e32 v26, v25
	v_div_scale_f32 v27, vcc, s5, v8, s5
	v_fma_f32 v28, -v25, v26, 1.0
	v_fmac_f32_e32 v26, v28, v26
	v_mul_f32_e32 v28, v27, v26
	v_fma_f32 v29, -v25, v28, v27
	v_fmac_f32_e32 v28, v29, v26
	v_fma_f32 v25, -v25, v28, v27
	v_div_fmas_f32 v25, v25, v26, v28
	v_div_fixup_f32 v31, v25, v8, s5
	v_cndmask_b32_e64 v31, 1.0, v31, s[12:13]
	v_mul_f32_e32 v188, v188, v31
	v_mul_f32_e32 v189, v189, v31
	v_mul_f32_e32 v190, v190, v31
	v_mul_f32_e32 v191, v191, v31
	v_mul_f32_e32 v192, v192, v31
	v_mul_f32_e32 v193, v193, v31
	v_mul_f32_e32 v194, v194, v31
	v_mul_f32_e32 v195, v195, v31
	v_mul_f32_e32 v196, v196, v31
	v_mul_f32_e32 v197, v197, v31
	v_mul_f32_e32 v198, v198, v31
	v_mul_f32_e32 v199, v199, v31
	v_mul_f32_e32 v200, v200, v31
	v_mul_f32_e32 v201, v201, v31
	v_mul_f32_e32 v202, v202, v31
	v_mul_f32_e32 v203, v203, v31
	v_cvt_pk_fp8_f32 v188, v188, v189
	v_cvt_pk_fp8_f32 v192, v192, v193
	v_cvt_pk_fp8_f32 v196, v196, v197
	v_cvt_pk_fp8_f32 v200, v200, v201
	v_cvt_pk_fp8_f32 v188, v190, v191 op_sel:[0,0,1]
	v_cvt_pk_fp8_f32 v192, v194, v195 op_sel:[0,0,1]
	v_cvt_pk_fp8_f32 v196, v198, v199 op_sel:[0,0,1]
	v_cvt_pk_fp8_f32 v200, v202, v203 op_sel:[0,0,1]
	global_store_dword v[12:13], v188, off
	global_store_dword v[12:13], v192, off offset:256
	global_store_dword v[12:13], v196, off offset:512
	global_store_dword v[12:13], v200, off offset:768
	v_lshl_add_u64 v[12:13], v[12:13], 0, s[100:101]
	global_load_dwordx4 v[188:191], v[14:15], off
	global_load_dwordx4 v[192:195], v[14:15], off offset:1024
	global_load_dwordx4 v[196:199], v[14:15], off offset:2048
	global_load_dwordx4 v[200:203], v[14:15], off offset:3072
	v_lshl_add_u64 v[14:15], v[14:15], 0, s[98:99]
	v_cmp_lt_f32_e64 s[12:13], 0, v9
	v_div_scale_f32 v25, s[6:7], s5, s5, v9
	v_rcp_f32_e32 v26, v25
	v_div_scale_f32 v27, vcc, v9, s5, v9
	v_fma_f32 v28, -v25, v26, 1.0
	v_fmac_f32_e32 v26, v28, v26
	v_mul_f32_e32 v28, v27, v26
	v_fma_f32 v29, -v25, v28, v27
	v_fmac_f32_e32 v28, v29, v26
	v_fma_f32 v25, -v25, v28, v27
	v_div_fmas_f32 v25, v25, v26, v28
	v_div_fixup_f32 v30, v25, s5, v9
	v_cndmask_b32_e64 v30, 1.0, v30, s[12:13]
	v_add_u32_e32 v17, 0xe000, v16
	s_and_saveexec_b64 s[54:55], s[10:11]
	global_store_dword v17, v30, s[34:35]
	s_or_b64 exec, exec, s[54:55]
	v_div_scale_f32 v25, s[6:7], v9, v9, s5
	v_rcp_f32_e32 v26, v25
	v_div_scale_f32 v27, vcc, s5, v9, s5
	v_fma_f32 v28, -v25, v26, 1.0
	v_fmac_f32_e32 v26, v28, v26
	v_mul_f32_e32 v28, v27, v26
	v_fma_f32 v29, -v25, v28, v27
	v_fmac_f32_e32 v28, v29, v26
	v_fma_f32 v25, -v25, v28, v27
	v_div_fmas_f32 v25, v25, v26, v28
	v_div_fixup_f32 v31, v25, v9, s5
	v_cndmask_b32_e64 v31, 1.0, v31, s[12:13]
	v_mul_f32_e32 v204, v204, v31
	v_mul_f32_e32 v205, v205, v31
	v_mul_f32_e32 v206, v206, v31
	v_mul_f32_e32 v207, v207, v31
	v_mul_f32_e32 v208, v208, v31
	v_mul_f32_e32 v209, v209, v31
	v_mul_f32_e32 v210, v210, v31
	v_mul_f32_e32 v211, v211, v31
	v_mul_f32_e32 v212, v212, v31
	v_mul_f32_e32 v213, v213, v31
	v_mul_f32_e32 v214, v214, v31
	v_mul_f32_e32 v215, v215, v31
	v_mul_f32_e32 v228, v228, v31
	v_mul_f32_e32 v229, v229, v31
	v_mul_f32_e32 v230, v230, v31
	v_mul_f32_e32 v231, v231, v31
	v_cvt_pk_fp8_f32 v204, v204, v205
	v_cvt_pk_fp8_f32 v208, v208, v209
	v_cvt_pk_fp8_f32 v212, v212, v213
	v_cvt_pk_fp8_f32 v228, v228, v229
	v_cvt_pk_fp8_f32 v204, v206, v207 op_sel:[0,0,1]
	v_cvt_pk_fp8_f32 v208, v210, v211 op_sel:[0,0,1]
	v_cvt_pk_fp8_f32 v212, v214, v215 op_sel:[0,0,1]
	v_cvt_pk_fp8_f32 v228, v230, v231 op_sel:[0,0,1]
	global_store_dword v[12:13], v204, off
	global_store_dword v[12:13], v208, off offset:256
	global_store_dword v[12:13], v212, off offset:512
	global_store_dword v[12:13], v228, off offset:768
	global_load_dwordx4 v[204:207], v[14:15], off
	global_load_dwordx4 v[208:211], v[14:15], off offset:1024
	global_load_dwordx4 v[212:215], v[14:15], off offset:2048
	global_load_dwordx4 v[228:231], v[14:15], off offset:3072
	v_lshlrev_b32_e32 v12, 10, v226
	v_mov_b32_e32 v13, 0
	v_lshl_add_u64 v[12:13], v[170:171], 0, v[12:13]
	s_waitcnt vmcnt(63)
; DI void fp8_rows(const float* __restrict__ src, unsigned char* __restrict__ dst, float* __restrict__ rs, int nrows) {
;     ...
;     for (int i = 0; i < 4; ++i) {
;       v[i] = *(const float4*)(src + (size_t)row * 1024 + 4 * lane + 256 * i);
;       am = fmaxf(am, fmaxf(fmaxf(fabsf(v[i].x), fabsf(v[i].y)), fmaxf(fabsf(v[i].z), fabsf(v[i].w))));
;     }
;     am = fmaxf(am, __shfl_xor(am, 32)); am = fmaxf(am, __shfl_xor(am, 16)); am = fmaxf(am, __shfl_xor(am, 8));
;     am = fmaxf(am, __shfl_xor(am, 4)); am = fmaxf(am, __shfl_xor(am, 2)); am = fmaxf(am, __shfl_xor(am, 1));
	v_max3_f32 v2, |v80|, |v81|, 0
	v_max3_f32 v2, |v82|, |v83|, v2
	v_max3_f32 v2, |v84|, |v85|, v2
	v_max3_f32 v2, |v86|, |v87|, v2
	v_max3_f32 v2, |v88|, |v89|, v2
	v_max3_f32 v2, |v90|, |v91|, v2
	v_max3_f32 v2, |v92|, |v93|, v2
	v_max3_f32 v2, |v94|, |v95|, v2
	s_nop 1
	v_max_f32_dpp v2, v2, v2 quad_perm:[1,0,3,2] row_mask:0xf bank_mask:0xf
	s_nop 1
	v_max_f32_dpp v2, v2, v2 quad_perm:[2,3,0,1] row_mask:0xf bank_mask:0xf
	s_nop 1
	v_max_f32_dpp v2, v2, v2 row_half_mirror row_mask:0xf bank_mask:0xf
	s_nop 1
	v_max_f32_dpp v2, v2, v2 row_mirror row_mask:0xf bank_mask:0xf
	v_mov_b32_e32 v17, v2
	s_nop 1
	v_permlane16_swap_b32_e32 v2, v17
	v_max_f32_e32 v2, v2, v17
	v_mov_b32_e32 v17, v2
	s_nop 1
	v_permlane32_swap_b32_e32 v2, v17
	v_max_f32_e32 v2, v2, v17
	s_waitcnt vmcnt(54)
	v_max3_f32 v3, |v96|, |v97|, 0
	v_max3_f32 v3, |v98|, |v99|, v3
	v_max3_f32 v3, |v100|, |v101|, v3
	v_max3_f32 v3, |v102|, |v103|, v3
	v_max3_f32 v3, |v104|, |v105|, v3
	v_max3_f32 v3, |v106|, |v107|, v3
	v_max3_f32 v3, |v108|, |v109|, v3
	v_max3_f32 v3, |v110|, |v111|, v3
	s_nop 1
	v_max_f32_dpp v3, v3, v3 quad_perm:[1,0,3,2] row_mask:0xf bank_mask:0xf
	s_nop 1
	v_max_f32_dpp v3, v3, v3 quad_perm:[2,3,0,1] row_mask:0xf bank_mask:0xf
	s_nop 1
	v_max_f32_dpp v3, v3, v3 row_half_mirror row_mask:0xf bank_mask:0xf
	s_nop 1
	v_max_f32_dpp v3, v3, v3 row_mirror row_mask:0xf bank_mask:0xf
	v_mov_b32_e32 v17, v3
	s_nop 1
	v_permlane16_swap_b32_e32 v3, v17
	v_max_f32_e32 v3, v3, v17
	v_mov_b32_e32 v17, v3
	s_nop 1
	v_permlane32_swap_b32_e32 v3, v17
	v_max_f32_e32 v3, v3, v17
	s_waitcnt vmcnt(45)
	v_max3_f32 v4, |v112|, |v113|, 0
	v_max3_f32 v4, |v114|, |v115|, v4
	v_max3_f32 v4, |v116|, |v117|, v4
	v_max3_f32 v4, |v118|, |v119|, v4
	v_max3_f32 v4, |v120|, |v121|, v4
	v_max3_f32 v4, |v122|, |v123|, v4
	v_max3_f32 v4, |v124|, |v125|, v4
	v_max3_f32 v4, |v126|, |v127|, v4
	s_nop 1
	v_max_f32_dpp v4, v4, v4 quad_perm:[1,0,3,2] row_mask:0xf bank_mask:0xf
	s_nop 1
	v_max_f32_dpp v4, v4, v4 quad_perm:[2,3,0,1] row_mask:0xf bank_mask:0xf
	s_nop 1
	v_max_f32_dpp v4, v4, v4 row_half_mirror row_mask:0xf bank_mask:0xf
	s_nop 1
	v_max_f32_dpp v4, v4, v4 row_mirror row_mask:0xf bank_mask:0xf
	v_mov_b32_e32 v17, v4
	s_nop 1
	v_permlane16_swap_b32_e32 v4, v17
	v_max_f32_e32 v4, v4, v17
	v_mov_b32_e32 v17, v4
	s_nop 1
	v_permlane32_swap_b32_e32 v4, v17
	v_max_f32_e32 v4, v4, v17
	s_waitcnt vmcnt(36)
	v_max3_f32 v5, |v128|, |v129|, 0
	v_max3_f32 v5, |v130|, |v131|, v5
	v_max3_f32 v5, |v132|, |v133|, v5
	v_max3_f32 v5, |v134|, |v135|, v5
	v_max3_f32 v5, |v136|, |v137|, v5
	v_max3_f32 v5, |v138|, |v139|, v5
	v_max3_f32 v5, |v140|, |v141|, v5
	v_max3_f32 v5, |v142|, |v143|, v5
	s_nop 1
	v_max_f32_dpp v5, v5, v5 quad_perm:[1,0,3,2] row_mask:0xf bank_mask:0xf
	s_nop 1
	v_max_f32_dpp v5, v5, v5 quad_perm:[2,3,0,1] row_mask:0xf bank_mask:0xf
	s_nop 1
	v_max_f32_dpp v5, v5, v5 row_half_mirror row_mask:0xf bank_mask:0xf
	s_nop 1
	v_max_f32_dpp v5, v5, v5 row_mirror row_mask:0xf bank_mask:0xf
	v_mov_b32_e32 v17, v5
	s_nop 1
	v_permlane16_swap_b32_e32 v5, v17
	v_max_f32_e32 v5, v5, v17
	v_mov_b32_e32 v17, v5
	s_nop 1
	v_permlane32_swap_b32_e32 v5, v17
	v_max_f32_e32 v5, v5, v17
	s_waitcnt vmcnt(27)
	v_max3_f32 v6, |v144|, |v145|, 0
	v_max3_f32 v6, |v146|, |v147|, v6
	v_max3_f32 v6, |v148|, |v149|, v6
	v_max3_f32 v6, |v150|, |v151|, v6
	v_max3_f32 v6, |v152|, |v153|, v6
	v_max3_f32 v6, |v154|, |v155|, v6
	v_max3_f32 v6, |v156|, |v157|, v6
	v_max3_f32 v6, |v158|, |v159|, v6
	s_nop 1
	v_max_f32_dpp v6, v6, v6 quad_perm:[1,0,3,2] row_mask:0xf bank_mask:0xf
	s_nop 1
	v_max_f32_dpp v6, v6, v6 quad_perm:[2,3,0,1] row_mask:0xf bank_mask:0xf
	s_nop 1
	v_max_f32_dpp v6, v6, v6 row_half_mirror row_mask:0xf bank_mask:0xf
	s_nop 1
	v_max_f32_dpp v6, v6, v6 row_mirror row_mask:0xf bank_mask:0xf
	v_mov_b32_e32 v17, v6
	s_nop 1
	v_permlane16_swap_b32_e32 v6, v17
	v_max_f32_e32 v6, v6, v17
	v_mov_b32_e32 v17, v6
	s_nop 1
	v_permlane32_swap_b32_e32 v6, v17
	v_max_f32_e32 v6, v6, v17
	s_waitcnt vmcnt(18)
	v_max3_f32 v7, |v172|, |v173|, 0
	v_max3_f32 v7, |v174|, |v175|, v7
	v_max3_f32 v7, |v176|, |v177|, v7
	v_max3_f32 v7, |v178|, |v179|, v7
	v_max3_f32 v7, |v180|, |v181|, v7
	v_max3_f32 v7, |v182|, |v183|, v7
	v_max3_f32 v7, |v184|, |v185|, v7
	v_max3_f32 v7, |v186|, |v187|, v7
	s_nop 1
	v_max_f32_dpp v7, v7, v7 quad_perm:[1,0,3,2] row_mask:0xf bank_mask:0xf
	s_nop 1
	v_max_f32_dpp v7, v7, v7 quad_perm:[2,3,0,1] row_mask:0xf bank_mask:0xf
	s_nop 1
	v_max_f32_dpp v7, v7, v7 row_half_mirror row_mask:0xf bank_mask:0xf
	s_nop 1
	v_max_f32_dpp v7, v7, v7 row_mirror row_mask:0xf bank_mask:0xf
	v_mov_b32_e32 v17, v7
	s_nop 1
	v_permlane16_swap_b32_e32 v7, v17
	v_max_f32_e32 v7, v7, v17
	v_mov_b32_e32 v17, v7
	s_nop 1
	v_permlane32_swap_b32_e32 v7, v17
	v_max_f32_e32 v7, v7, v17
	s_waitcnt vmcnt(9)
	v_max3_f32 v8, |v188|, |v189|, 0
	v_max3_f32 v8, |v190|, |v191|, v8
	v_max3_f32 v8, |v192|, |v193|, v8
	v_max3_f32 v8, |v194|, |v195|, v8
	v_max3_f32 v8, |v196|, |v197|, v8
	v_max3_f32 v8, |v198|, |v199|, v8
	v_max3_f32 v8, |v200|, |v201|, v8
	v_max3_f32 v8, |v202|, |v203|, v8
	s_nop 1
	v_max_f32_dpp v8, v8, v8 quad_perm:[1,0,3,2] row_mask:0xf bank_mask:0xf
	s_nop 1
	v_max_f32_dpp v8, v8, v8 quad_perm:[2,3,0,1] row_mask:0xf bank_mask:0xf
	s_nop 1
	v_max_f32_dpp v8, v8, v8 row_half_mirror row_mask:0xf bank_mask:0xf
	s_nop 1
	v_max_f32_dpp v8, v8, v8 row_mirror row_mask:0xf bank_mask:0xf
	v_mov_b32_e32 v17, v8
	s_nop 1
	v_permlane16_swap_b32_e32 v8, v17
	v_max_f32_e32 v8, v8, v17
	v_mov_b32_e32 v17, v8
	s_nop 1
	v_permlane32_swap_b32_e32 v8, v17
	v_max_f32_e32 v8, v8, v17
	s_waitcnt vmcnt(0)
; DI void fp8_rows(const float* __restrict__ src, unsigned char* __restrict__ dst, float* __restrict__ rs, int nrows) {
;     ...
;     for (int i = 0; i < 4; ++i) {
;       v[i] = *(const float4*)(src + (size_t)row * 1024 + 4 * lane + 256 * i);
;       am = fmaxf(am, fmaxf(fmaxf(fabsf(v[i].x), fabsf(v[i].y)), fmaxf(fabsf(v[i].z), fabsf(v[i].w))));
;     }
;     am = fmaxf(am, __shfl_xor(am, 32)); am = fmaxf(am, __shfl_xor(am, 16)); am = fmaxf(am, __shfl_xor(am, 8));
;     am = fmaxf(am, __shfl_xor(am, 4)); am = fmaxf(am, __shfl_xor(am, 2)); am = fmaxf(am, __shfl_xor(am, 1));
;     const float sc = am > 0.f ? 440.f / am : 1.f;
;     if (lane == 0) rs[row] = am > 0.f ? am / 440.f : 1.f;
; #pragma unroll
;     for (int i = 0; i < 4; ++i) {
;       int pk = __builtin_amdgcn_cvt_pk_fp8_f32(v[i].x * sc, v[i].y * sc, 0, false);
;       pk = __builtin_amdgcn_cvt_pk_fp8_f32(v[i].z * sc, v[i].w * sc, pk, true);
;       *(int*)(dst + (size_t)row * 1024 + 4 * lane + 256 * i) = pk;
;     }
	v_max3_f32 v9, |v204|, |v205|, 0
	v_max3_f32 v9, |v206|, |v207|, v9
	v_max3_f32 v9, |v208|, |v209|, v9
	v_max3_f32 v9, |v210|, |v211|, v9
	v_max3_f32 v9, |v212|, |v213|, v9
	v_max3_f32 v9, |v214|, |v215|, v9
	v_max3_f32 v9, |v228|, |v229|, v9
	v_max3_f32 v9, |v230|, |v231|, v9
	s_nop 1
	v_max_f32_dpp v9, v9, v9 quad_perm:[1,0,3,2] row_mask:0xf bank_mask:0xf
	s_nop 1
	v_max_f32_dpp v9, v9, v9 quad_perm:[2,3,0,1] row_mask:0xf bank_mask:0xf
	s_nop 1
	v_max_f32_dpp v9, v9, v9 row_half_mirror row_mask:0xf bank_mask:0xf
	s_nop 1
	v_max_f32_dpp v9, v9, v9 row_mirror row_mask:0xf bank_mask:0xf
	v_mov_b32_e32 v17, v9
	s_nop 1
	v_permlane16_swap_b32_e32 v9, v17
	v_max_f32_e32 v9, v9, v17
	v_mov_b32_e32 v17, v9
	s_nop 1
	v_permlane32_swap_b32_e32 v9, v17
	v_max_f32_e32 v9, v9, v17
	v_cmp_lt_f32_e64 s[12:13], 0, v2
	v_div_scale_f32 v25, s[6:7], s5, s5, v2
	v_rcp_f32_e32 v26, v25
	v_div_scale_f32 v27, vcc, v2, s5, v2
	v_fma_f32 v28, -v25, v26, 1.0
	v_fmac_f32_e32 v26, v28, v26
	v_mul_f32_e32 v28, v27, v26
	v_fma_f32 v29, -v25, v28, v27
	v_fmac_f32_e32 v28, v29, v26
	v_fma_f32 v25, -v25, v28, v27
	v_div_fmas_f32 v25, v25, v26, v28
	v_div_fixup_f32 v30, v25, s5, v2
	v_cndmask_b32_e64 v30, 1.0, v30, s[12:13]
	v_mov_b32_e32 v17, v16
	s_and_saveexec_b64 s[54:55], s[10:11]
	global_store_dword v17, v30, s[42:43]
	s_or_b64 exec, exec, s[54:55]
	v_div_scale_f32 v25, s[6:7], v2, v2, s5
	v_rcp_f32_e32 v26, v25
	v_div_scale_f32 v27, vcc, s5, v2, s5
	v_fma_f32 v28, -v25, v26, 1.0
	v_fmac_f32_e32 v26, v28, v26
	v_mul_f32_e32 v28, v27, v26
	v_fma_f32 v29, -v25, v28, v27
	v_fmac_f32_e32 v28, v29, v26
	v_fma_f32 v25, -v25, v28, v27
	v_div_fmas_f32 v25, v25, v26, v28
	v_div_fixup_f32 v31, v25, v2, s5
	v_cndmask_b32_e64 v31, 1.0, v31, s[12:13]
	v_mul_f32_e32 v80, v80, v31
	v_mul_f32_e32 v81, v81, v31
	v_mul_f32_e32 v82, v82, v31
	v_mul_f32_e32 v83, v83, v31
	v_mul_f32_e32 v84, v84, v31
	v_mul_f32_e32 v85, v85, v31
	v_mul_f32_e32 v86, v86, v31
	v_mul_f32_e32 v87, v87, v31
	v_mul_f32_e32 v88, v88, v31
	v_mul_f32_e32 v89, v89, v31
	v_mul_f32_e32 v90, v90, v31
	v_mul_f32_e32 v91, v91, v31
	v_mul_f32_e32 v92, v92, v31
	v_mul_f32_e32 v93, v93, v31
	v_mul_f32_e32 v94, v94, v31
	v_mul_f32_e32 v95, v95, v31
	v_cvt_pk_fp8_f32 v80, v80, v81
	v_cvt_pk_fp8_f32 v84, v84, v85
	v_cvt_pk_fp8_f32 v88, v88, v89
	v_cvt_pk_fp8_f32 v92, v92, v93
	v_cvt_pk_fp8_f32 v80, v82, v83 op_sel:[0,0,1]
	v_cvt_pk_fp8_f32 v84, v86, v87 op_sel:[0,0,1]
	v_cvt_pk_fp8_f32 v88, v90, v91 op_sel:[0,0,1]
	v_cvt_pk_fp8_f32 v92, v94, v95 op_sel:[0,0,1]
	global_store_dword v[12:13], v80, off
	global_store_dword v[12:13], v84, off offset:256
	global_store_dword v[12:13], v88, off offset:512
	global_store_dword v[12:13], v92, off offset:768
	v_lshl_add_u64 v[12:13], v[12:13], 0, s[100:101]
	v_cmp_lt_f32_e64 s[12:13], 0, v3
	v_div_scale_f32 v25, s[6:7], s5, s5, v3
	v_rcp_f32_e32 v26, v25
	v_div_scale_f32 v27, vcc, v3, s5, v3
	v_fma_f32 v28, -v25, v26, 1.0
	v_fmac_f32_e32 v26, v28, v26
	v_mul_f32_e32 v28, v27, v26
	v_fma_f32 v29, -v25, v28, v27
	v_fmac_f32_e32 v28, v29, v26
	v_fma_f32 v25, -v25, v28, v27
	v_div_fmas_f32 v25, v25, v26, v28
	v_div_fixup_f32 v30, v25, s5, v3
	v_cndmask_b32_e64 v30, 1.0, v30, s[12:13]
	v_add_u32_e32 v17, 0x2000, v16
	s_and_saveexec_b64 s[54:55], s[10:11]
	global_store_dword v17, v30, s[42:43]
	s_or_b64 exec, exec, s[54:55]
	v_div_scale_f32 v25, s[6:7], v3, v3, s5
	v_rcp_f32_e32 v26, v25
	v_div_scale_f32 v27, vcc, s5, v3, s5
	v_fma_f32 v28, -v25, v26, 1.0
	v_fmac_f32_e32 v26, v28, v26
	v_mul_f32_e32 v28, v27, v26
	v_fma_f32 v29, -v25, v28, v27
	v_fmac_f32_e32 v28, v29, v26
	v_fma_f32 v25, -v25, v28, v27
	v_div_fmas_f32 v25, v25, v26, v28
	v_div_fixup_f32 v31, v25, v3, s5
	v_cndmask_b32_e64 v31, 1.0, v31, s[12:13]
	v_mul_f32_e32 v96, v96, v31
	v_mul_f32_e32 v97, v97, v31
	v_mul_f32_e32 v98, v98, v31
	v_mul_f32_e32 v99, v99, v31
	v_mul_f32_e32 v100, v100, v31
	v_mul_f32_e32 v101, v101, v31
	v_mul_f32_e32 v102, v102, v31
	v_mul_f32_e32 v103, v103, v31
	v_mul_f32_e32 v104, v104, v31
	v_mul_f32_e32 v105, v105, v31
	v_mul_f32_e32 v106, v106, v31
	v_mul_f32_e32 v107, v107, v31
	v_mul_f32_e32 v108, v108, v31
	v_mul_f32_e32 v109, v109, v31
	v_mul_f32_e32 v110, v110, v31
	v_mul_f32_e32 v111, v111, v31
	v_cvt_pk_fp8_f32 v96, v96, v97
	v_cvt_pk_fp8_f32 v100, v100, v101
	v_cvt_pk_fp8_f32 v104, v104, v105
	v_cvt_pk_fp8_f32 v108, v108, v109
	v_cvt_pk_fp8_f32 v96, v98, v99 op_sel:[0,0,1]
	v_cvt_pk_fp8_f32 v100, v102, v103 op_sel:[0,0,1]
	v_cvt_pk_fp8_f32 v104, v106, v107 op_sel:[0,0,1]
	v_cvt_pk_fp8_f32 v108, v110, v111 op_sel:[0,0,1]
	global_store_dword v[12:13], v96, off
	global_store_dword v[12:13], v100, off offset:256
	global_store_dword v[12:13], v104, off offset:512
	global_store_dword v[12:13], v108, off offset:768
	v_lshl_add_u64 v[12:13], v[12:13], 0, s[100:101]
	v_cmp_lt_f32_e64 s[12:13], 0, v4
	v_div_scale_f32 v25, s[6:7], s5, s5, v4
	v_rcp_f32_e32 v26, v25
	v_div_scale_f32 v27, vcc, v4, s5, v4
	v_fma_f32 v28, -v25, v26, 1.0
	v_fmac_f32_e32 v26, v28, v26
	v_mul_f32_e32 v28, v27, v26
	v_fma_f32 v29, -v25, v28, v27
	v_fmac_f32_e32 v28, v29, v26
	v_fma_f32 v25, -v25, v28, v27
	v_div_fmas_f32 v25, v25, v26, v28
	v_div_fixup_f32 v30, v25, s5, v4
	v_cndmask_b32_e64 v30, 1.0, v30, s[12:13]
	v_add_u32_e32 v17, 0x4000, v16
	s_and_saveexec_b64 s[54:55], s[10:11]
	global_store_dword v17, v30, s[42:43]
	s_or_b64 exec, exec, s[54:55]
	v_div_scale_f32 v25, s[6:7], v4, v4, s5
	v_rcp_f32_e32 v26, v25
	v_div_scale_f32 v27, vcc, s5, v4, s5
	v_fma_f32 v28, -v25, v26, 1.0
	v_fmac_f32_e32 v26, v28, v26
	v_mul_f32_e32 v28, v27, v26
	v_fma_f32 v29, -v25, v28, v27
	v_fmac_f32_e32 v28, v29, v26
	v_fma_f32 v25, -v25, v28, v27
; DI void fp8_rows(const float* __restrict__ src, unsigned char* __restrict__ dst, float* __restrict__ rs, int nrows) {
;     ...
;     const float sc = am > 0.f ? 440.f / am : 1.f;
;     if (lane == 0) rs[row] = am > 0.f ? am / 440.f : 1.f;
; #pragma unroll
;     for (int i = 0; i < 4; ++i) {
;       int pk = __builtin_amdgcn_cvt_pk_fp8_f32(v[i].x * sc, v[i].y * sc, 0, false);
;       pk = __builtin_amdgcn_cvt_pk_fp8_f32(v[i].z * sc, v[i].w * sc, pk, true);
;       *(int*)(dst + (size_t)row * 1024 + 4 * lane + 256 * i) = pk;
;     }
	v_div_fmas_f32 v25, v25, v26, v28
	v_div_fixup_f32 v31, v25, v4, s5
	v_cndmask_b32_e64 v31, 1.0, v31, s[12:13]
	v_mul_f32_e32 v112, v112, v31
	v_mul_f32_e32 v113, v113, v31
	v_mul_f32_e32 v114, v114, v31
	v_mul_f32_e32 v115, v115, v31
	v_mul_f32_e32 v116, v116, v31
	v_mul_f32_e32 v117, v117, v31
	v_mul_f32_e32 v118, v118, v31
	v_mul_f32_e32 v119, v119, v31
	v_mul_f32_e32 v120, v120, v31
	v_mul_f32_e32 v121, v121, v31
	v_mul_f32_e32 v122, v122, v31
	v_mul_f32_e32 v123, v123, v31
	v_mul_f32_e32 v124, v124, v31
	v_mul_f32_e32 v125, v125, v31
	v_mul_f32_e32 v126, v126, v31
	v_mul_f32_e32 v127, v127, v31
	v_cvt_pk_fp8_f32 v112, v112, v113
	v_cvt_pk_fp8_f32 v116, v116, v117
	v_cvt_pk_fp8_f32 v120, v120, v121
	v_cvt_pk_fp8_f32 v124, v124, v125
	v_cvt_pk_fp8_f32 v112, v114, v115 op_sel:[0,0,1]
	v_cvt_pk_fp8_f32 v116, v118, v119 op_sel:[0,0,1]
	v_cvt_pk_fp8_f32 v120, v122, v123 op_sel:[0,0,1]
	v_cvt_pk_fp8_f32 v124, v126, v127 op_sel:[0,0,1]
	global_store_dword v[12:13], v112, off
	global_store_dword v[12:13], v116, off offset:256
	global_store_dword v[12:13], v120, off offset:512
	global_store_dword v[12:13], v124, off offset:768
	v_lshl_add_u64 v[12:13], v[12:13], 0, s[100:101]
	v_cmp_lt_f32_e64 s[12:13], 0, v5
	v_div_scale_f32 v25, s[6:7], s5, s5, v5
	v_rcp_f32_e32 v26, v25
	v_div_scale_f32 v27, vcc, v5, s5, v5
	v_fma_f32 v28, -v25, v26, 1.0
	v_fmac_f32_e32 v26, v28, v26
	v_mul_f32_e32 v28, v27, v26
	v_fma_f32 v29, -v25, v28, v27
	v_fmac_f32_e32 v28, v29, v26
	v_fma_f32 v25, -v25, v28, v27
	v_div_fmas_f32 v25, v25, v26, v28
	v_div_fixup_f32 v30, v25, s5, v5
	v_cndmask_b32_e64 v30, 1.0, v30, s[12:13]
	v_add_u32_e32 v17, 0x6000, v16
	s_and_saveexec_b64 s[54:55], s[10:11]
	global_store_dword v17, v30, s[42:43]
	s_or_b64 exec, exec, s[54:55]
	v_div_scale_f32 v25, s[6:7], v5, v5, s5
	v_rcp_f32_e32 v26, v25
	v_div_scale_f32 v27, vcc, s5, v5, s5
	v_fma_f32 v28, -v25, v26, 1.0
	v_fmac_f32_e32 v26, v28, v26
	v_mul_f32_e32 v28, v27, v26
	v_fma_f32 v29, -v25, v28, v27
	v_fmac_f32_e32 v28, v29, v26
	v_fma_f32 v25, -v25, v28, v27
	v_div_fmas_f32 v25, v25, v26, v28
	v_div_fixup_f32 v31, v25, v5, s5
	v_cndmask_b32_e64 v31, 1.0, v31, s[12:13]
	v_mul_f32_e32 v128, v128, v31
	v_mul_f32_e32 v129, v129, v31
	v_mul_f32_e32 v130, v130, v31
	v_mul_f32_e32 v131, v131, v31
	v_mul_f32_e32 v132, v132, v31
	v_mul_f32_e32 v133, v133, v31
	v_mul_f32_e32 v134, v134, v31
	v_mul_f32_e32 v135, v135, v31
	v_mul_f32_e32 v136, v136, v31
	v_mul_f32_e32 v137, v137, v31
	v_mul_f32_e32 v138, v138, v31
	v_mul_f32_e32 v139, v139, v31
	v_mul_f32_e32 v140, v140, v31
	v_mul_f32_e32 v141, v141, v31
	v_mul_f32_e32 v142, v142, v31
	v_mul_f32_e32 v143, v143, v31
	v_cvt_pk_fp8_f32 v128, v128, v129
	v_cvt_pk_fp8_f32 v132, v132, v133
	v_cvt_pk_fp8_f32 v136, v136, v137
	v_cvt_pk_fp8_f32 v140, v140, v141
	v_cvt_pk_fp8_f32 v128, v130, v131 op_sel:[0,0,1]
	v_cvt_pk_fp8_f32 v132, v134, v135 op_sel:[0,0,1]
	v_cvt_pk_fp8_f32 v136, v138, v139 op_sel:[0,0,1]
	v_cvt_pk_fp8_f32 v140, v142, v143 op_sel:[0,0,1]
	global_store_dword v[12:13], v128, off
	global_store_dword v[12:13], v132, off offset:256
	global_store_dword v[12:13], v136, off offset:512
	global_store_dword v[12:13], v140, off offset:768
	v_lshl_add_u64 v[12:13], v[12:13], 0, s[100:101]
	v_cmp_lt_f32_e64 s[12:13], 0, v6
	v_div_scale_f32 v25, s[6:7], s5, s5, v6
	v_rcp_f32_e32 v26, v25
	v_div_scale_f32 v27, vcc, v6, s5, v6
	v_fma_f32 v28, -v25, v26, 1.0
	v_fmac_f32_e32 v26, v28, v26
	v_mul_f32_e32 v28, v27, v26
	v_fma_f32 v29, -v25, v28, v27
	v_fmac_f32_e32 v28, v29, v26
	v_fma_f32 v25, -v25, v28, v27
	v_div_fmas_f32 v25, v25, v26, v28
	v_div_fixup_f32 v30, v25, s5, v6
	v_cndmask_b32_e64 v30, 1.0, v30, s[12:13]
	v_add_u32_e32 v17, 0x8000, v16
	s_and_saveexec_b64 s[54:55], s[10:11]
	global_store_dword v17, v30, s[42:43]
	s_or_b64 exec, exec, s[54:55]
	v_div_scale_f32 v25, s[6:7], v6, v6, s5
	v_rcp_f32_e32 v26, v25
	v_div_scale_f32 v27, vcc, s5, v6, s5
	v_fma_f32 v28, -v25, v26, 1.0
	v_fmac_f32_e32 v26, v28, v26
	v_mul_f32_e32 v28, v27, v26
	v_fma_f32 v29, -v25, v28, v27
	v_fmac_f32_e32 v28, v29, v26
	v_fma_f32 v25, -v25, v28, v27
	v_div_fmas_f32 v25, v25, v26, v28
	v_div_fixup_f32 v31, v25, v6, s5
	v_cndmask_b32_e64 v31, 1.0, v31, s[12:13]
	v_mul_f32_e32 v144, v144, v31
	v_mul_f32_e32 v145, v145, v31
	v_mul_f32_e32 v146, v146, v31
	v_mul_f32_e32 v147, v147, v31
	v_mul_f32_e32 v148, v148, v31
	v_mul_f32_e32 v149, v149, v31
	v_mul_f32_e32 v150, v150, v31
	v_mul_f32_e32 v151, v151, v31
	v_mul_f32_e32 v152, v152, v31
	v_mul_f32_e32 v153, v153, v31
	v_mul_f32_e32 v154, v154, v31
	v_mul_f32_e32 v155, v155, v31
	v_mul_f32_e32 v156, v156, v31
	v_mul_f32_e32 v157, v157, v31
	v_mul_f32_e32 v158, v158, v31
	v_mul_f32_e32 v159, v159, v31
	v_cvt_pk_fp8_f32 v144, v144, v145
	v_cvt_pk_fp8_f32 v148, v148, v149
	v_cvt_pk_fp8_f32 v152, v152, v153
	v_cvt_pk_fp8_f32 v156, v156, v157
	v_cvt_pk_fp8_f32 v144, v146, v147 op_sel:[0,0,1]
	v_cvt_pk_fp8_f32 v148, v150, v151 op_sel:[0,0,1]
	v_cvt_pk_fp8_f32 v152, v154, v155 op_sel:[0,0,1]
	v_cvt_pk_fp8_f32 v156, v158, v159 op_sel:[0,0,1]
	global_store_dword v[12:13], v144, off
	global_store_dword v[12:13], v148, off offset:256
	global_store_dword v[12:13], v152, off offset:512
	global_store_dword v[12:13], v156, off offset:768
	v_lshl_add_u64 v[12:13], v[12:13], 0, s[100:101]
	v_cmp_lt_f32_e64 s[12:13], 0, v7
	v_div_scale_f32 v25, s[6:7], s5, s5, v7
	v_rcp_f32_e32 v26, v25
	v_div_scale_f32 v27, vcc, v7, s5, v7
	v_fma_f32 v28, -v25, v26, 1.0
	v_fmac_f32_e32 v26, v28, v26
	v_mul_f32_e32 v28, v27, v26
	v_fma_f32 v29, -v25, v28, v27
	v_fmac_f32_e32 v28, v29, v26
	v_fma_f32 v25, -v25, v28, v27
	v_div_fmas_f32 v25, v25, v26, v28
; DI void fp8_rows(const float* __restrict__ src, unsigned char* __restrict__ dst, float* __restrict__ rs, int nrows) {
;     ...
;     const float sc = am > 0.f ? 440.f / am : 1.f;
;     if (lane == 0) rs[row] = am > 0.f ? am / 440.f : 1.f;
; #pragma unroll
;     for (int i = 0; i < 4; ++i) {
;       int pk = __builtin_amdgcn_cvt_pk_fp8_f32(v[i].x * sc, v[i].y * sc, 0, false);
;       pk = __builtin_amdgcn_cvt_pk_fp8_f32(v[i].z * sc, v[i].w * sc, pk, true);
;       *(int*)(dst + (size_t)row * 1024 + 4 * lane + 256 * i) = pk;
;     }
	v_div_fixup_f32 v30, v25, s5, v7
	v_cndmask_b32_e64 v30, 1.0, v30, s[12:13]
	v_add_u32_e32 v17, 0xa000, v16
	s_and_saveexec_b64 s[54:55], s[10:11]
	global_store_dword v17, v30, s[42:43]
	s_or_b64 exec, exec, s[54:55]
	v_div_scale_f32 v25, s[6:7], v7, v7, s5
	v_rcp_f32_e32 v26, v25
	v_div_scale_f32 v27, vcc, s5, v7, s5
	v_fma_f32 v28, -v25, v26, 1.0
	v_fmac_f32_e32 v26, v28, v26
	v_mul_f32_e32 v28, v27, v26
	v_fma_f32 v29, -v25, v28, v27
	v_fmac_f32_e32 v28, v29, v26
	v_fma_f32 v25, -v25, v28, v27
	v_div_fmas_f32 v25, v25, v26, v28
	v_div_fixup_f32 v31, v25, v7, s5
	v_cndmask_b32_e64 v31, 1.0, v31, s[12:13]
	v_mul_f32_e32 v172, v172, v31
	v_mul_f32_e32 v173, v173, v31
	v_mul_f32_e32 v174, v174, v31
	v_mul_f32_e32 v175, v175, v31
	v_mul_f32_e32 v176, v176, v31
	v_mul_f32_e32 v177, v177, v31
	v_mul_f32_e32 v178, v178, v31
	v_mul_f32_e32 v179, v179, v31
	v_mul_f32_e32 v180, v180, v31
	v_mul_f32_e32 v181, v181, v31
	v_mul_f32_e32 v182, v182, v31
	v_mul_f32_e32 v183, v183, v31
	v_mul_f32_e32 v184, v184, v31
	v_mul_f32_e32 v185, v185, v31
	v_mul_f32_e32 v186, v186, v31
	v_mul_f32_e32 v187, v187, v31
	v_cvt_pk_fp8_f32 v172, v172, v173
	v_cvt_pk_fp8_f32 v176, v176, v177
	v_cvt_pk_fp8_f32 v180, v180, v181
	v_cvt_pk_fp8_f32 v184, v184, v185
	v_cvt_pk_fp8_f32 v172, v174, v175 op_sel:[0,0,1]
	v_cvt_pk_fp8_f32 v176, v178, v179 op_sel:[0,0,1]
	v_cvt_pk_fp8_f32 v180, v182, v183 op_sel:[0,0,1]
	v_cvt_pk_fp8_f32 v184, v186, v187 op_sel:[0,0,1]
	global_store_dword v[12:13], v172, off
	global_store_dword v[12:13], v176, off offset:256
	global_store_dword v[12:13], v180, off offset:512
	global_store_dword v[12:13], v184, off offset:768
	v_lshl_add_u64 v[12:13], v[12:13], 0, s[100:101]
	v_cmp_lt_f32_e64 s[12:13], 0, v8
	v_div_scale_f32 v25, s[6:7], s5, s5, v8
	v_rcp_f32_e32 v26, v25
	v_div_scale_f32 v27, vcc, v8, s5, v8
	v_fma_f32 v28, -v25, v26, 1.0
	v_fmac_f32_e32 v26, v28, v26
	v_mul_f32_e32 v28, v27, v26
	v_fma_f32 v29, -v25, v28, v27
	v_fmac_f32_e32 v28, v29, v26
	v_fma_f32 v25, -v25, v28, v27
	v_div_fmas_f32 v25, v25, v26, v28
	v_div_fixup_f32 v30, v25, s5, v8
	v_cndmask_b32_e64 v30, 1.0, v30, s[12:13]
	v_add_u32_e32 v17, 0xc000, v16
	s_and_saveexec_b64 s[54:55], s[10:11]
	global_store_dword v17, v30, s[42:43]
	s_or_b64 exec, exec, s[54:55]
	v_div_scale_f32 v25, s[6:7], v8, v8, s5
	v_rcp_f32_e32 v26, v25
	v_div_scale_f32 v27, vcc, s5, v8, s5
	v_fma_f32 v28, -v25, v26, 1.0
	v_fmac_f32_e32 v26, v28, v26
	v_mul_f32_e32 v28, v27, v26
	v_fma_f32 v29, -v25, v28, v27
	v_fmac_f32_e32 v28, v29, v26
	v_fma_f32 v25, -v25, v28, v27
	v_div_fmas_f32 v25, v25, v26, v28
	v_div_fixup_f32 v31, v25, v8, s5
	v_cndmask_b32_e64 v31, 1.0, v31, s[12:13]
	v_mul_f32_e32 v188, v188, v31
	v_mul_f32_e32 v189, v189, v31
	v_mul_f32_e32 v190, v190, v31
	v_mul_f32_e32 v191, v191, v31
	v_mul_f32_e32 v192, v192, v31
	v_mul_f32_e32 v193, v193, v31
	v_mul_f32_e32 v194, v194, v31
	v_mul_f32_e32 v195, v195, v31
	v_mul_f32_e32 v196, v196, v31
	v_mul_f32_e32 v197, v197, v31
	v_mul_f32_e32 v198, v198, v31
	v_mul_f32_e32 v199, v199, v31
	v_mul_f32_e32 v200, v200, v31
	v_mul_f32_e32 v201, v201, v31
	v_mul_f32_e32 v202, v202, v31
	v_mul_f32_e32 v203, v203, v31
	v_cvt_pk_fp8_f32 v188, v188, v189
	v_cvt_pk_fp8_f32 v192, v192, v193
	v_cvt_pk_fp8_f32 v196, v196, v197
	v_cvt_pk_fp8_f32 v200, v200, v201
	v_cvt_pk_fp8_f32 v188, v190, v191 op_sel:[0,0,1]
	v_cvt_pk_fp8_f32 v192, v194, v195 op_sel:[0,0,1]
	v_cvt_pk_fp8_f32 v196, v198, v199 op_sel:[0,0,1]
	v_cvt_pk_fp8_f32 v200, v202, v203 op_sel:[0,0,1]
	global_store_dword v[12:13], v188, off
	global_store_dword v[12:13], v192, off offset:256
	global_store_dword v[12:13], v196, off offset:512
	global_store_dword v[12:13], v200, off offset:768
	v_lshl_add_u64 v[12:13], v[12:13], 0, s[100:101]
	v_cmp_lt_f32_e64 s[12:13], 0, v9
	v_div_scale_f32 v25, s[6:7], s5, s5, v9
	v_rcp_f32_e32 v26, v25
	v_div_scale_f32 v27, vcc, v9, s5, v9
	v_fma_f32 v28, -v25, v26, 1.0
	v_fmac_f32_e32 v26, v28, v26
	v_mul_f32_e32 v28, v27, v26
	v_fma_f32 v29, -v25, v28, v27
	v_fmac_f32_e32 v28, v29, v26
	v_fma_f32 v25, -v25, v28, v27
	v_div_fmas_f32 v25, v25, v26, v28
	v_div_fixup_f32 v30, v25, s5, v9
	v_cndmask_b32_e64 v30, 1.0, v30, s[12:13]
	v_add_u32_e32 v17, 0xe000, v16
	s_and_saveexec_b64 s[54:55], s[10:11]
	global_store_dword v17, v30, s[42:43]
	s_or_b64 exec, exec, s[54:55]
	v_div_scale_f32 v25, s[6:7], v9, v9, s5
	v_rcp_f32_e32 v26, v25
	v_div_scale_f32 v27, vcc, s5, v9, s5
	v_fma_f32 v28, -v25, v26, 1.0
	v_fmac_f32_e32 v26, v28, v26
	v_mul_f32_e32 v28, v27, v26
	v_fma_f32 v29, -v25, v28, v27
	v_fmac_f32_e32 v28, v29, v26
	v_fma_f32 v25, -v25, v28, v27
	v_div_fmas_f32 v25, v25, v26, v28
	v_div_fixup_f32 v31, v25, v9, s5
	v_cndmask_b32_e64 v31, 1.0, v31, s[12:13]
	v_mul_f32_e32 v204, v204, v31
	v_mul_f32_e32 v205, v205, v31
	v_mul_f32_e32 v206, v206, v31
	v_mul_f32_e32 v207, v207, v31
	v_mul_f32_e32 v208, v208, v31
	v_mul_f32_e32 v209, v209, v31
	v_mul_f32_e32 v210, v210, v31
	v_mul_f32_e32 v211, v211, v31
	v_mul_f32_e32 v212, v212, v31
	v_mul_f32_e32 v213, v213, v31
	v_mul_f32_e32 v214, v214, v31
	v_mul_f32_e32 v215, v215, v31
	v_mul_f32_e32 v228, v228, v31
	v_mul_f32_e32 v229, v229, v31
	v_mul_f32_e32 v230, v230, v31
	v_mul_f32_e32 v231, v231, v31
	v_cvt_pk_fp8_f32 v204, v204, v205
	v_cvt_pk_fp8_f32 v208, v208, v209
	v_cvt_pk_fp8_f32 v212, v212, v213
	v_cvt_pk_fp8_f32 v228, v228, v229
	v_cvt_pk_fp8_f32 v204, v206, v207 op_sel:[0,0,1]
	v_cvt_pk_fp8_f32 v208, v210, v211 op_sel:[0,0,1]
	v_cvt_pk_fp8_f32 v212, v214, v215 op_sel:[0,0,1]
	v_cvt_pk_fp8_f32 v228, v230, v231 op_sel:[0,0,1]
	global_store_dword v[12:13], v204, off
	global_store_dword v[12:13], v208, off offset:256
	global_store_dword v[12:13], v212, off offset:512
	global_store_dword v[12:13], v228, off offset:768
	s_branch .LBB0_415
.Lmy_fp8o_0:
	v_cmp_lt_i32_e32 vcc, v223, v218
	s_mov_b64 s[52:53], 0
	v_mov_b32_e32 v18, v226
	v_cndmask_b32_e32 v1, v161, v223, vcc
	v_cmp_lt_i32_e32 vcc, v224, v218
	v_lshlrev_b32_e32 v1, 2, v1
	s_nop 0
	v_cndmask_b32_e32 v2, v161, v224, vcc
	v_cmp_lt_i32_e32 vcc, v222, v218
	v_lshlrev_b32_e32 v20, 2, v2
	s_nop 0
	v_cndmask_b32_e32 v2, v161, v222, vcc
	v_cmp_lt_i32_e32 vcc, v221, v218
	v_lshlrev_b32_e32 v21, 2, v2
	s_nop 0
	v_cndmask_b32_e32 v2, v161, v221, vcc
	v_cmp_lt_i32_e32 vcc, v220, v218
	v_lshlrev_b32_e32 v22, 2, v2
	s_nop 0
	v_cndmask_b32_e32 v2, v161, v220, vcc
	v_cmp_lt_i32_e32 vcc, v219, v218
	v_lshlrev_b32_e32 v23, 2, v2
	s_nop 0
	v_cndmask_b32_e32 v2, v161, v219, vcc
	v_lshlrev_b32_e32 v24, 2, v2
	s_branch .LBB0_408

; DI void fp8_rows(const float* __restrict__ src, unsigned char* __restrict__ dst, float* __restrict__ rs, int nrows) {
;   const int lane = threadIdx.x & 63, w = threadIdx.x >> 6;
;   for (int row = blockIdx.x * 4 + w; row < nrows; row += gridDim.x * 4) {
;     float4 v[4];
;     float am = 0.f;
; #pragma unroll
;     for (int i = 0; i < 4; ++i) {
;       v[i] = *(const float4*)(src + (size_t)row * 1024 + 4 * lane + 256 * i);
;       am = fmaxf(am, fmaxf(fmaxf(fabsf(v[i].x), fabsf(v[i].y)), fmaxf(fabsf(v[i].z), fabsf(v[i].w))));
;     }
;     am = fmaxf(am, __shfl_xor(am, 32)); am = fmaxf(am, __shfl_xor(am, 16)); am = fmaxf(am, __shfl_xor(am, 8));
;     am = fmaxf(am, __shfl_xor(am, 4)); am = fmaxf(am, __shfl_xor(am, 2)); am = fmaxf(am, __shfl_xor(am, 1));
.LBB0_594:
	s_and_b64 vcc, exec, s[56:57]
	s_mov_b64 s[12:13], -1
	s_cbranch_vccnz .LBB0_606
	s_and_saveexec_b64 s[4:5], s[8:9]
	s_xor_b64 s[12:13], exec, s[4:5]
	s_andn2_saveexec_b64 s[14:15], s[12:13]
	s_cbranch_execz .LBB0_605
	s_cmp_lg_u32 s26, 0x200
	s_cbranch_scc1 .Lmy_fp8o_1
	s_mov_b32 s98, 0x800000
	s_mov_b32 s99, 0
	s_mov_b32 s100, 0x200000
	s_mov_b32 s101, 0
	v_lshlrev_b32_e32 v14, 2, v226
	v_lshlrev_b32_e32 v8, 12, v226
	v_mov_b32_e32 v9, 0
	v_lshl_add_u64 v[8:9], v[130:131], 0, v[8:9]
	global_load_dwordx4 v[32:35], v[8:9], off
	global_load_dwordx4 v[36:39], v[8:9], off offset:1024
	global_load_dwordx4 v[40:43], v[8:9], off offset:2048
	global_load_dwordx4 v[44:47], v[8:9], off offset:3072
	v_lshl_add_u64 v[8:9], v[8:9], 0, s[98:99]
	global_load_dwordx4 v[48:51], v[8:9], off
	global_load_dwordx4 v[52:55], v[8:9], off offset:1024
	global_load_dwordx4 v[56:59], v[8:9], off offset:2048
	global_load_dwordx4 v[60:63], v[8:9], off offset:3072
	v_lshl_add_u64 v[8:9], v[8:9], 0, s[98:99]
	global_load_dwordx4 v[64:67], v[8:9], off
	global_load_dwordx4 v[68:71], v[8:9], off offset:1024
	global_load_dwordx4 v[72:75], v[8:9], off offset:2048
	global_load_dwordx4 v[76:79], v[8:9], off offset:3072
	v_lshl_add_u64 v[8:9], v[8:9], 0, s[98:99]
	global_load_dwordx4 v[80:83], v[8:9], off
	global_load_dwordx4 v[84:87], v[8:9], off offset:1024
	global_load_dwordx4 v[88:91], v[8:9], off offset:2048
	global_load_dwordx4 v[92:95], v[8:9], off offset:3072
	v_lshl_add_u64 v[8:9], v[8:9], 0, s[98:99]
	global_load_dwordx4 v[96:99], v[8:9], off
	global_load_dwordx4 v[100:103], v[8:9], off offset:1024
	global_load_dwordx4 v[104:107], v[8:9], off offset:2048
	global_load_dwordx4 v[108:111], v[8:9], off offset:3072
	v_lshl_add_u64 v[8:9], v[8:9], 0, s[98:99]
	global_load_dwordx4 v[112:115], v[8:9], off
	global_load_dwordx4 v[116:119], v[8:9], off offset:1024
	global_load_dwordx4 v[120:123], v[8:9], off offset:2048
	global_load_dwordx4 v[124:127], v[8:9], off offset:3072
	v_lshl_add_u64 v[8:9], v[8:9], 0, s[98:99]
	global_load_dwordx4 v[172:175], v[8:9], off
	global_load_dwordx4 v[176:179], v[8:9], off offset:1024
	global_load_dwordx4 v[180:183], v[8:9], off offset:2048
	global_load_dwordx4 v[184:187], v[8:9], off offset:3072
	v_lshl_add_u64 v[8:9], v[8:9], 0, s[98:99]
	global_load_dwordx4 v[188:191], v[8:9], off
	global_load_dwordx4 v[192:195], v[8:9], off offset:1024
	global_load_dwordx4 v[196:199], v[8:9], off offset:2048
	global_load_dwordx4 v[200:203], v[8:9], off offset:3072
	v_lshlrev_b32_e32 v12, 12, v226
	v_mov_b32_e32 v13, 0
	v_lshl_add_u64 v[12:13], v[134:135], 0, v[12:13]
	v_lshlrev_b32_e32 v10, 10, v226
	v_mov_b32_e32 v11, 0
	v_lshl_add_u64 v[10:11], v[132:133], 0, v[10:11]
	s_waitcnt vmcnt(28)
	v_max3_f32 v0, |v32|, |v33|, 0
	v_max3_f32 v0, |v34|, |v35|, v0
	v_max3_f32 v0, |v36|, |v37|, v0
	v_max3_f32 v0, |v38|, |v39|, v0
	v_max3_f32 v0, |v40|, |v41|, v0
	v_max3_f32 v0, |v42|, |v43|, v0
	v_max3_f32 v0, |v44|, |v45|, v0
	v_max3_f32 v0, |v46|, |v47|, v0
	s_nop 1
	v_max_f32_dpp v0, v0, v0 quad_perm:[1,0,3,2] row_mask:0xf bank_mask:0xf
	s_nop 1
	v_max_f32_dpp v0, v0, v0 quad_perm:[2,3,0,1] row_mask:0xf bank_mask:0xf
	s_nop 1
	v_max_f32_dpp v0, v0, v0 row_half_mirror row_mask:0xf bank_mask:0xf
	s_nop 1
	v_max_f32_dpp v0, v0, v0 row_mirror row_mask:0xf bank_mask:0xf
	v_mov_b32_e32 v15, v0
	s_nop 1
	v_permlane16_swap_b32_e32 v0, v15
	v_max_f32_e32 v0, v0, v15
	v_mov_b32_e32 v15, v0
	s_nop 1
	v_permlane32_swap_b32_e32 v0, v15
	v_max_f32_e32 v0, v0, v15
	s_waitcnt vmcnt(24)
	v_max3_f32 v1, |v48|, |v49|, 0
	v_max3_f32 v1, |v50|, |v51|, v1
	v_max3_f32 v1, |v52|, |v53|, v1
	v_max3_f32 v1, |v54|, |v55|, v1
	v_max3_f32 v1, |v56|, |v57|, v1
	v_max3_f32 v1, |v58|, |v59|, v1
	v_max3_f32 v1, |v60|, |v61|, v1
	v_max3_f32 v1, |v62|, |v63|, v1
	s_nop 1
	v_max_f32_dpp v1, v1, v1 quad_perm:[1,0,3,2] row_mask:0xf bank_mask:0xf
	s_nop 1
	v_max_f32_dpp v1, v1, v1 quad_perm:[2,3,0,1] row_mask:0xf bank_mask:0xf
	s_nop 1
	v_max_f32_dpp v1, v1, v1 row_half_mirror row_mask:0xf bank_mask:0xf
	s_nop 1
	v_max_f32_dpp v1, v1, v1 row_mirror row_mask:0xf bank_mask:0xf
	v_mov_b32_e32 v15, v1
	s_nop 1
	v_permlane16_swap_b32_e32 v1, v15
	v_max_f32_e32 v1, v1, v15
	v_mov_b32_e32 v15, v1
	s_nop 1
	v_permlane32_swap_b32_e32 v1, v15
	v_max_f32_e32 v1, v1, v15
	s_waitcnt vmcnt(20)
	v_max3_f32 v2, |v64|, |v65|, 0
	v_max3_f32 v2, |v66|, |v67|, v2
	v_max3_f32 v2, |v68|, |v69|, v2
	v_max3_f32 v2, |v70|, |v71|, v2
	v_max3_f32 v2, |v72|, |v73|, v2
	v_max3_f32 v2, |v74|, |v75|, v2
	v_max3_f32 v2, |v76|, |v77|, v2
	v_max3_f32 v2, |v78|, |v79|, v2
	s_nop 1
	v_max_f32_dpp v2, v2, v2 quad_perm:[1,0,3,2] row_mask:0xf bank_mask:0xf
	s_nop 1
	v_max_f32_dpp v2, v2, v2 quad_perm:[2,3,0,1] row_mask:0xf bank_mask:0xf
	s_nop 1
	v_max_f32_dpp v2, v2, v2 row_half_mirror row_mask:0xf bank_mask:0xf
	s_nop 1
	v_max_f32_dpp v2, v2, v2 row_mirror row_mask:0xf bank_mask:0xf
	v_mov_b32_e32 v15, v2
	s_nop 1
	v_permlane16_swap_b32_e32 v2, v15
	v_max_f32_e32 v2, v2, v15
	v_mov_b32_e32 v15, v2
	s_nop 1
	v_permlane32_swap_b32_e32 v2, v15
	v_max_f32_e32 v2, v2, v15
	s_waitcnt vmcnt(16)
	v_max3_f32 v3, |v80|, |v81|, 0
	v_max3_f32 v3, |v82|, |v83|, v3
	v_max3_f32 v3, |v84|, |v85|, v3
	v_max3_f32 v3, |v86|, |v87|, v3
	v_max3_f32 v3, |v88|, |v89|, v3
	v_max3_f32 v3, |v90|, |v91|, v3
	v_max3_f32 v3, |v92|, |v93|, v3
	v_max3_f32 v3, |v94|, |v95|, v3
	s_nop 1
	v_max_f32_dpp v3, v3, v3 quad_perm:[1,0,3,2] row_mask:0xf bank_mask:0xf
	s_nop 1
	v_max_f32_dpp v3, v3, v3 quad_perm:[2,3,0,1] row_mask:0xf bank_mask:0xf
	s_nop 1
	v_max_f32_dpp v3, v3, v3 row_half_mirror row_mask:0xf bank_mask:0xf
	s_nop 1
	v_max_f32_dpp v3, v3, v3 row_mirror row_mask:0xf bank_mask:0xf
	v_mov_b32_e32 v15, v3
	s_nop 1
	v_permlane16_swap_b32_e32 v3, v15
	v_max_f32_e32 v3, v3, v15
	v_mov_b32_e32 v15, v3
	s_nop 1
	v_permlane32_swap_b32_e32 v3, v15
	v_max_f32_e32 v3, v3, v15
	s_waitcnt vmcnt(12)
; DI void fp8_rows(const float* __restrict__ src, unsigned char* __restrict__ dst, float* __restrict__ rs, int nrows) {
;     ...
;     for (int i = 0; i < 4; ++i) {
;       v[i] = *(const float4*)(src + (size_t)row * 1024 + 4 * lane + 256 * i);
;       am = fmaxf(am, fmaxf(fmaxf(fabsf(v[i].x), fabsf(v[i].y)), fmaxf(fabsf(v[i].z), fabsf(v[i].w))));
;     }
;     am = fmaxf(am, __shfl_xor(am, 32)); am = fmaxf(am, __shfl_xor(am, 16)); am = fmaxf(am, __shfl_xor(am, 8));
;     am = fmaxf(am, __shfl_xor(am, 4)); am = fmaxf(am, __shfl_xor(am, 2)); am = fmaxf(am, __shfl_xor(am, 1));
;     const float sc = am > 0.f ? 440.f / am : 1.f;
;     if (lane == 0) rs[row] = am > 0.f ? am / 440.f : 1.f;
; #pragma unroll
;     for (int i = 0; i < 4; ++i) {
;       int pk = __builtin_amdgcn_cvt_pk_fp8_f32(v[i].x * sc, v[i].y * sc, 0, false);
;       pk = __builtin_amdgcn_cvt_pk_fp8_f32(v[i].z * sc, v[i].w * sc, pk, true);
;       *(int*)(dst + (size_t)row * 1024 + 4 * lane + 256 * i) = pk;
;     }
	v_max3_f32 v4, |v96|, |v97|, 0
	v_max3_f32 v4, |v98|, |v99|, v4
	v_max3_f32 v4, |v100|, |v101|, v4
	v_max3_f32 v4, |v102|, |v103|, v4
	v_max3_f32 v4, |v104|, |v105|, v4
	v_max3_f32 v4, |v106|, |v107|, v4
	v_max3_f32 v4, |v108|, |v109|, v4
	v_max3_f32 v4, |v110|, |v111|, v4
	s_nop 1
	v_max_f32_dpp v4, v4, v4 quad_perm:[1,0,3,2] row_mask:0xf bank_mask:0xf
	s_nop 1
	v_max_f32_dpp v4, v4, v4 quad_perm:[2,3,0,1] row_mask:0xf bank_mask:0xf
	s_nop 1
	v_max_f32_dpp v4, v4, v4 row_half_mirror row_mask:0xf bank_mask:0xf
	s_nop 1
	v_max_f32_dpp v4, v4, v4 row_mirror row_mask:0xf bank_mask:0xf
	v_mov_b32_e32 v15, v4
	s_nop 1
	v_permlane16_swap_b32_e32 v4, v15
	v_max_f32_e32 v4, v4, v15
	v_mov_b32_e32 v15, v4
	s_nop 1
	v_permlane32_swap_b32_e32 v4, v15
	v_max_f32_e32 v4, v4, v15
	s_waitcnt vmcnt(8)
	v_max3_f32 v5, |v112|, |v113|, 0
	v_max3_f32 v5, |v114|, |v115|, v5
	v_max3_f32 v5, |v116|, |v117|, v5
	v_max3_f32 v5, |v118|, |v119|, v5
	v_max3_f32 v5, |v120|, |v121|, v5
	v_max3_f32 v5, |v122|, |v123|, v5
	v_max3_f32 v5, |v124|, |v125|, v5
	v_max3_f32 v5, |v126|, |v127|, v5
	s_nop 1
	v_max_f32_dpp v5, v5, v5 quad_perm:[1,0,3,2] row_mask:0xf bank_mask:0xf
	s_nop 1
	v_max_f32_dpp v5, v5, v5 quad_perm:[2,3,0,1] row_mask:0xf bank_mask:0xf
	s_nop 1
	v_max_f32_dpp v5, v5, v5 row_half_mirror row_mask:0xf bank_mask:0xf
	s_nop 1
	v_max_f32_dpp v5, v5, v5 row_mirror row_mask:0xf bank_mask:0xf
	v_mov_b32_e32 v15, v5
	s_nop 1
	v_permlane16_swap_b32_e32 v5, v15
	v_max_f32_e32 v5, v5, v15
	v_mov_b32_e32 v15, v5
	s_nop 1
	v_permlane32_swap_b32_e32 v5, v15
	v_max_f32_e32 v5, v5, v15
	s_waitcnt vmcnt(4)
	v_max3_f32 v6, |v172|, |v173|, 0
	v_max3_f32 v6, |v174|, |v175|, v6
	v_max3_f32 v6, |v176|, |v177|, v6
	v_max3_f32 v6, |v178|, |v179|, v6
	v_max3_f32 v6, |v180|, |v181|, v6
	v_max3_f32 v6, |v182|, |v183|, v6
	v_max3_f32 v6, |v184|, |v185|, v6
	v_max3_f32 v6, |v186|, |v187|, v6
	s_nop 1
	v_max_f32_dpp v6, v6, v6 quad_perm:[1,0,3,2] row_mask:0xf bank_mask:0xf
	s_nop 1
	v_max_f32_dpp v6, v6, v6 quad_perm:[2,3,0,1] row_mask:0xf bank_mask:0xf
	s_nop 1
	v_max_f32_dpp v6, v6, v6 row_half_mirror row_mask:0xf bank_mask:0xf
	s_nop 1
	v_max_f32_dpp v6, v6, v6 row_mirror row_mask:0xf bank_mask:0xf
	v_mov_b32_e32 v15, v6
	s_nop 1
	v_permlane16_swap_b32_e32 v6, v15
	v_max_f32_e32 v6, v6, v15
	v_mov_b32_e32 v15, v6
	s_nop 1
	v_permlane32_swap_b32_e32 v6, v15
	v_max_f32_e32 v6, v6, v15
	s_waitcnt vmcnt(0)
	v_max3_f32 v7, |v188|, |v189|, 0
	v_max3_f32 v7, |v190|, |v191|, v7
	v_max3_f32 v7, |v192|, |v193|, v7
	v_max3_f32 v7, |v194|, |v195|, v7
	v_max3_f32 v7, |v196|, |v197|, v7
	v_max3_f32 v7, |v198|, |v199|, v7
	v_max3_f32 v7, |v200|, |v201|, v7
	v_max3_f32 v7, |v202|, |v203|, v7
	s_nop 1
	v_max_f32_dpp v7, v7, v7 quad_perm:[1,0,3,2] row_mask:0xf bank_mask:0xf
	s_nop 1
	v_max_f32_dpp v7, v7, v7 quad_perm:[2,3,0,1] row_mask:0xf bank_mask:0xf
	s_nop 1
	v_max_f32_dpp v7, v7, v7 row_half_mirror row_mask:0xf bank_mask:0xf
	s_nop 1
	v_max_f32_dpp v7, v7, v7 row_mirror row_mask:0xf bank_mask:0xf
	v_mov_b32_e32 v15, v7
	s_nop 1
	v_permlane16_swap_b32_e32 v7, v15
	v_max_f32_e32 v7, v7, v15
	v_mov_b32_e32 v15, v7
	s_nop 1
	v_permlane32_swap_b32_e32 v7, v15
	v_max_f32_e32 v7, v7, v15
	v_cmp_lt_f32_e64 s[12:13], 0, v0
	v_div_scale_f32 v24, s[4:5], s64, s64, v0
	v_rcp_f32_e32 v25, v24
	v_div_scale_f32 v26, vcc, v0, s64, v0
	v_fma_f32 v27, -v24, v25, 1.0
	v_fmac_f32_e32 v25, v27, v25
	v_mul_f32_e32 v27, v26, v25
	v_fma_f32 v28, -v24, v27, v26
	v_fmac_f32_e32 v27, v28, v25
	v_fma_f32 v24, -v24, v27, v26
	v_div_fmas_f32 v24, v24, v25, v27
	v_div_fixup_f32 v29, v24, s64, v0
	v_cndmask_b32_e64 v29, 1.0, v29, s[12:13]
	v_mov_b32_e32 v15, v14
	s_and_saveexec_b64 s[56:57], s[10:11]
	global_store_dword v15, v29, s[52:53]
	s_or_b64 exec, exec, s[56:57]
	v_div_scale_f32 v24, s[4:5], v0, v0, s64
	v_rcp_f32_e32 v25, v24
	v_div_scale_f32 v26, vcc, s64, v0, s64
	v_fma_f32 v27, -v24, v25, 1.0
	v_fmac_f32_e32 v25, v27, v25
	v_mul_f32_e32 v27, v26, v25
	v_fma_f32 v28, -v24, v27, v26
	v_fmac_f32_e32 v27, v28, v25
	v_fma_f32 v24, -v24, v27, v26
	v_div_fmas_f32 v24, v24, v25, v27
	v_div_fixup_f32 v30, v24, v0, s64
	v_cndmask_b32_e64 v30, 1.0, v30, s[12:13]
	v_mul_f32_e32 v32, v32, v30
	v_mul_f32_e32 v33, v33, v30
	v_mul_f32_e32 v34, v34, v30
	v_mul_f32_e32 v35, v35, v30
	v_mul_f32_e32 v36, v36, v30
	v_mul_f32_e32 v37, v37, v30
	v_mul_f32_e32 v38, v38, v30
	v_mul_f32_e32 v39, v39, v30
	v_mul_f32_e32 v40, v40, v30
	v_mul_f32_e32 v41, v41, v30
	v_mul_f32_e32 v42, v42, v30
	v_mul_f32_e32 v43, v43, v30
	v_mul_f32_e32 v44, v44, v30
	v_mul_f32_e32 v45, v45, v30
	v_mul_f32_e32 v46, v46, v30
	v_mul_f32_e32 v47, v47, v30
	v_cvt_pk_fp8_f32 v32, v32, v33
	v_cvt_pk_fp8_f32 v36, v36, v37
	v_cvt_pk_fp8_f32 v40, v40, v41
	v_cvt_pk_fp8_f32 v44, v44, v45
	v_cvt_pk_fp8_f32 v32, v34, v35 op_sel:[0,0,1]
	v_cvt_pk_fp8_f32 v36, v38, v39 op_sel:[0,0,1]
	v_cvt_pk_fp8_f32 v40, v42, v43 op_sel:[0,0,1]
	v_cvt_pk_fp8_f32 v44, v46, v47 op_sel:[0,0,1]
	global_store_dword v[10:11], v32, off
	global_store_dword v[10:11], v36, off offset:256
	global_store_dword v[10:11], v40, off offset:512
	global_store_dword v[10:11], v44, off offset:768
	v_lshl_add_u64 v[10:11], v[10:11], 0, s[100:101]
	global_load_dwordx4 v[32:35], v[12:13], off
	global_load_dwordx4 v[36:39], v[12:13], off offset:1024
	global_load_dwordx4 v[40:43], v[12:13], off offset:2048
	global_load_dwordx4 v[44:47], v[12:13], off offset:3072
	v_lshl_add_u64 v[12:13], v[12:13], 0, s[98:99]
	v_cmp_lt_f32_e64 s[12:13], 0, v1
	v_div_scale_f32 v24, s[4:5], s64, s64, v1
	v_rcp_f32_e32 v25, v24
	v_div_scale_f32 v26, vcc, v1, s64, v1
	v_fma_f32 v27, -v24, v25, 1.0
	v_fmac_f32_e32 v25, v27, v25
; DI void fp8_rows(const float* __restrict__ src, unsigned char* __restrict__ dst, float* __restrict__ rs, int nrows) {
;     ...
;     const float sc = am > 0.f ? 440.f / am : 1.f;
;     if (lane == 0) rs[row] = am > 0.f ? am / 440.f : 1.f;
; #pragma unroll
;     for (int i = 0; i < 4; ++i) {
;       int pk = __builtin_amdgcn_cvt_pk_fp8_f32(v[i].x * sc, v[i].y * sc, 0, false);
;       pk = __builtin_amdgcn_cvt_pk_fp8_f32(v[i].z * sc, v[i].w * sc, pk, true);
;       *(int*)(dst + (size_t)row * 1024 + 4 * lane + 256 * i) = pk;
;     }
	v_mul_f32_e32 v27, v26, v25
	v_fma_f32 v28, -v24, v27, v26
	v_fmac_f32_e32 v27, v28, v25
	v_fma_f32 v24, -v24, v27, v26
	v_div_fmas_f32 v24, v24, v25, v27
	v_div_fixup_f32 v29, v24, s64, v1
	v_cndmask_b32_e64 v29, 1.0, v29, s[12:13]
	v_add_u32_e32 v15, 0x2000, v14
	s_and_saveexec_b64 s[56:57], s[10:11]
	global_store_dword v15, v29, s[52:53]
	s_or_b64 exec, exec, s[56:57]
	v_div_scale_f32 v24, s[4:5], v1, v1, s64
	v_rcp_f32_e32 v25, v24
	v_div_scale_f32 v26, vcc, s64, v1, s64
	v_fma_f32 v27, -v24, v25, 1.0
	v_fmac_f32_e32 v25, v27, v25
	v_mul_f32_e32 v27, v26, v25
	v_fma_f32 v28, -v24, v27, v26
	v_fmac_f32_e32 v27, v28, v25
	v_fma_f32 v24, -v24, v27, v26
	v_div_fmas_f32 v24, v24, v25, v27
	v_div_fixup_f32 v30, v24, v1, s64
	v_cndmask_b32_e64 v30, 1.0, v30, s[12:13]
	v_mul_f32_e32 v48, v48, v30
	v_mul_f32_e32 v49, v49, v30
	v_mul_f32_e32 v50, v50, v30
	v_mul_f32_e32 v51, v51, v30
	v_mul_f32_e32 v52, v52, v30
	v_mul_f32_e32 v53, v53, v30
	v_mul_f32_e32 v54, v54, v30
	v_mul_f32_e32 v55, v55, v30
	v_mul_f32_e32 v56, v56, v30
	v_mul_f32_e32 v57, v57, v30
	v_mul_f32_e32 v58, v58, v30
	v_mul_f32_e32 v59, v59, v30
	v_mul_f32_e32 v60, v60, v30
	v_mul_f32_e32 v61, v61, v30
	v_mul_f32_e32 v62, v62, v30
	v_mul_f32_e32 v63, v63, v30
	v_cvt_pk_fp8_f32 v48, v48, v49
	v_cvt_pk_fp8_f32 v52, v52, v53
	v_cvt_pk_fp8_f32 v56, v56, v57
	v_cvt_pk_fp8_f32 v60, v60, v61
	v_cvt_pk_fp8_f32 v48, v50, v51 op_sel:[0,0,1]
	v_cvt_pk_fp8_f32 v52, v54, v55 op_sel:[0,0,1]
	v_cvt_pk_fp8_f32 v56, v58, v59 op_sel:[0,0,1]
	v_cvt_pk_fp8_f32 v60, v62, v63 op_sel:[0,0,1]
	global_store_dword v[10:11], v48, off
	global_store_dword v[10:11], v52, off offset:256
	global_store_dword v[10:11], v56, off offset:512
	global_store_dword v[10:11], v60, off offset:768
	v_lshl_add_u64 v[10:11], v[10:11], 0, s[100:101]
	global_load_dwordx4 v[48:51], v[12:13], off
	global_load_dwordx4 v[52:55], v[12:13], off offset:1024
	global_load_dwordx4 v[56:59], v[12:13], off offset:2048
	global_load_dwordx4 v[60:63], v[12:13], off offset:3072
	v_lshl_add_u64 v[12:13], v[12:13], 0, s[98:99]
	v_cmp_lt_f32_e64 s[12:13], 0, v2
	v_div_scale_f32 v24, s[4:5], s64, s64, v2
	v_rcp_f32_e32 v25, v24
	v_div_scale_f32 v26, vcc, v2, s64, v2
	v_fma_f32 v27, -v24, v25, 1.0
	v_fmac_f32_e32 v25, v27, v25
	v_mul_f32_e32 v27, v26, v25
	v_fma_f32 v28, -v24, v27, v26
	v_fmac_f32_e32 v27, v28, v25
	v_fma_f32 v24, -v24, v27, v26
	v_div_fmas_f32 v24, v24, v25, v27
	v_div_fixup_f32 v29, v24, s64, v2
	v_cndmask_b32_e64 v29, 1.0, v29, s[12:13]
	v_add_u32_e32 v15, 0x4000, v14
	s_and_saveexec_b64 s[56:57], s[10:11]
	global_store_dword v15, v29, s[52:53]
	s_or_b64 exec, exec, s[56:57]
	v_div_scale_f32 v24, s[4:5], v2, v2, s64
	v_rcp_f32_e32 v25, v24
	v_div_scale_f32 v26, vcc, s64, v2, s64
	v_fma_f32 v27, -v24, v25, 1.0
	v_fmac_f32_e32 v25, v27, v25
	v_mul_f32_e32 v27, v26, v25
	v_fma_f32 v28, -v24, v27, v26
	v_fmac_f32_e32 v27, v28, v25
	v_fma_f32 v24, -v24, v27, v26
	v_div_fmas_f32 v24, v24, v25, v27
	v_div_fixup_f32 v30, v24, v2, s64
	v_cndmask_b32_e64 v30, 1.0, v30, s[12:13]
	v_mul_f32_e32 v64, v64, v30
	v_mul_f32_e32 v65, v65, v30
	v_mul_f32_e32 v66, v66, v30
	v_mul_f32_e32 v67, v67, v30
	v_mul_f32_e32 v68, v68, v30
	v_mul_f32_e32 v69, v69, v30
	v_mul_f32_e32 v70, v70, v30
	v_mul_f32_e32 v71, v71, v30
	v_mul_f32_e32 v72, v72, v30
	v_mul_f32_e32 v73, v73, v30
	v_mul_f32_e32 v74, v74, v30
	v_mul_f32_e32 v75, v75, v30
	v_mul_f32_e32 v76, v76, v30
	v_mul_f32_e32 v77, v77, v30
	v_mul_f32_e32 v78, v78, v30
	v_mul_f32_e32 v79, v79, v30
	v_cvt_pk_fp8_f32 v64, v64, v65
	v_cvt_pk_fp8_f32 v68, v68, v69
	v_cvt_pk_fp8_f32 v72, v72, v73
	v_cvt_pk_fp8_f32 v76, v76, v77
	v_cvt_pk_fp8_f32 v64, v66, v67 op_sel:[0,0,1]
	v_cvt_pk_fp8_f32 v68, v70, v71 op_sel:[0,0,1]
	v_cvt_pk_fp8_f32 v72, v74, v75 op_sel:[0,0,1]
	v_cvt_pk_fp8_f32 v76, v78, v79 op_sel:[0,0,1]
	global_store_dword v[10:11], v64, off
	global_store_dword v[10:11], v68, off offset:256
	global_store_dword v[10:11], v72, off offset:512
	global_store_dword v[10:11], v76, off offset:768
	v_lshl_add_u64 v[10:11], v[10:11], 0, s[100:101]
	global_load_dwordx4 v[64:67], v[12:13], off
	global_load_dwordx4 v[68:71], v[12:13], off offset:1024
	global_load_dwordx4 v[72:75], v[12:13], off offset:2048
	global_load_dwordx4 v[76:79], v[12:13], off offset:3072
	v_lshl_add_u64 v[12:13], v[12:13], 0, s[98:99]
	v_cmp_lt_f32_e64 s[12:13], 0, v3
	v_div_scale_f32 v24, s[4:5], s64, s64, v3
	v_rcp_f32_e32 v25, v24
	v_div_scale_f32 v26, vcc, v3, s64, v3
	v_fma_f32 v27, -v24, v25, 1.0
	v_fmac_f32_e32 v25, v27, v25
	v_mul_f32_e32 v27, v26, v25
	v_fma_f32 v28, -v24, v27, v26
	v_fmac_f32_e32 v27, v28, v25
	v_fma_f32 v24, -v24, v27, v26
	v_div_fmas_f32 v24, v24, v25, v27
	v_div_fixup_f32 v29, v24, s64, v3
	v_cndmask_b32_e64 v29, 1.0, v29, s[12:13]
	v_add_u32_e32 v15, 0x6000, v14
	s_and_saveexec_b64 s[56:57], s[10:11]
	global_store_dword v15, v29, s[52:53]
	s_or_b64 exec, exec, s[56:57]
	v_div_scale_f32 v24, s[4:5], v3, v3, s64
	v_rcp_f32_e32 v25, v24
	v_div_scale_f32 v26, vcc, s64, v3, s64
	v_fma_f32 v27, -v24, v25, 1.0
	v_fmac_f32_e32 v25, v27, v25
	v_mul_f32_e32 v27, v26, v25
	v_fma_f32 v28, -v24, v27, v26
	v_fmac_f32_e32 v27, v28, v25
	v_fma_f32 v24, -v24, v27, v26
	v_div_fmas_f32 v24, v24, v25, v27
	v_div_fixup_f32 v30, v24, v3, s64
	v_cndmask_b32_e64 v30, 1.0, v30, s[12:13]
	v_mul_f32_e32 v80, v80, v30
	v_mul_f32_e32 v81, v81, v30
	v_mul_f32_e32 v82, v82, v30
	v_mul_f32_e32 v83, v83, v30
	v_mul_f32_e32 v84, v84, v30
	v_mul_f32_e32 v85, v85, v30
	v_mul_f32_e32 v86, v86, v30
	v_mul_f32_e32 v87, v87, v30
	v_mul_f32_e32 v88, v88, v30
	v_mul_f32_e32 v89, v89, v30
	v_mul_f32_e32 v90, v90, v30
	v_mul_f32_e32 v91, v91, v30
; DI void fp8_rows(const float* __restrict__ src, unsigned char* __restrict__ dst, float* __restrict__ rs, int nrows) {
;     ...
;     const float sc = am > 0.f ? 440.f / am : 1.f;
;     if (lane == 0) rs[row] = am > 0.f ? am / 440.f : 1.f;
; #pragma unroll
;     for (int i = 0; i < 4; ++i) {
;       int pk = __builtin_amdgcn_cvt_pk_fp8_f32(v[i].x * sc, v[i].y * sc, 0, false);
;       pk = __builtin_amdgcn_cvt_pk_fp8_f32(v[i].z * sc, v[i].w * sc, pk, true);
;       *(int*)(dst + (size_t)row * 1024 + 4 * lane + 256 * i) = pk;
;     }
	v_mul_f32_e32 v92, v92, v30
	v_mul_f32_e32 v93, v93, v30
	v_mul_f32_e32 v94, v94, v30
	v_mul_f32_e32 v95, v95, v30
	v_cvt_pk_fp8_f32 v80, v80, v81
	v_cvt_pk_fp8_f32 v84, v84, v85
	v_cvt_pk_fp8_f32 v88, v88, v89
	v_cvt_pk_fp8_f32 v92, v92, v93
	v_cvt_pk_fp8_f32 v80, v82, v83 op_sel:[0,0,1]
	v_cvt_pk_fp8_f32 v84, v86, v87 op_sel:[0,0,1]
	v_cvt_pk_fp8_f32 v88, v90, v91 op_sel:[0,0,1]
	v_cvt_pk_fp8_f32 v92, v94, v95 op_sel:[0,0,1]
	global_store_dword v[10:11], v80, off
	global_store_dword v[10:11], v84, off offset:256
	global_store_dword v[10:11], v88, off offset:512
	global_store_dword v[10:11], v92, off offset:768
	v_lshl_add_u64 v[10:11], v[10:11], 0, s[100:101]
	global_load_dwordx4 v[80:83], v[12:13], off
	global_load_dwordx4 v[84:87], v[12:13], off offset:1024
	global_load_dwordx4 v[88:91], v[12:13], off offset:2048
	global_load_dwordx4 v[92:95], v[12:13], off offset:3072
	v_lshl_add_u64 v[12:13], v[12:13], 0, s[98:99]
	v_cmp_lt_f32_e64 s[12:13], 0, v4
	v_div_scale_f32 v24, s[4:5], s64, s64, v4
	v_rcp_f32_e32 v25, v24
	v_div_scale_f32 v26, vcc, v4, s64, v4
	v_fma_f32 v27, -v24, v25, 1.0
	v_fmac_f32_e32 v25, v27, v25
	v_mul_f32_e32 v27, v26, v25
	v_fma_f32 v28, -v24, v27, v26
	v_fmac_f32_e32 v27, v28, v25
	v_fma_f32 v24, -v24, v27, v26
	v_div_fmas_f32 v24, v24, v25, v27
	v_div_fixup_f32 v29, v24, s64, v4
	v_cndmask_b32_e64 v29, 1.0, v29, s[12:13]
	v_add_u32_e32 v15, 0x8000, v14
	s_and_saveexec_b64 s[56:57], s[10:11]
	global_store_dword v15, v29, s[52:53]
	s_or_b64 exec, exec, s[56:57]
	v_div_scale_f32 v24, s[4:5], v4, v4, s64
	v_rcp_f32_e32 v25, v24
	v_div_scale_f32 v26, vcc, s64, v4, s64
	v_fma_f32 v27, -v24, v25, 1.0
	v_fmac_f32_e32 v25, v27, v25
	v_mul_f32_e32 v27, v26, v25
	v_fma_f32 v28, -v24, v27, v26
	v_fmac_f32_e32 v27, v28, v25
	v_fma_f32 v24, -v24, v27, v26
	v_div_fmas_f32 v24, v24, v25, v27
	v_div_fixup_f32 v30, v24, v4, s64
	v_cndmask_b32_e64 v30, 1.0, v30, s[12:13]
	v_mul_f32_e32 v96, v96, v30
	v_mul_f32_e32 v97, v97, v30
	v_mul_f32_e32 v98, v98, v30
	v_mul_f32_e32 v99, v99, v30
	v_mul_f32_e32 v100, v100, v30
	v_mul_f32_e32 v101, v101, v30
	v_mul_f32_e32 v102, v102, v30
	v_mul_f32_e32 v103, v103, v30
	v_mul_f32_e32 v104, v104, v30
	v_mul_f32_e32 v105, v105, v30
	v_mul_f32_e32 v106, v106, v30
	v_mul_f32_e32 v107, v107, v30
	v_mul_f32_e32 v108, v108, v30
	v_mul_f32_e32 v109, v109, v30
	v_mul_f32_e32 v110, v110, v30
	v_mul_f32_e32 v111, v111, v30
	v_cvt_pk_fp8_f32 v96, v96, v97
	v_cvt_pk_fp8_f32 v100, v100, v101
	v_cvt_pk_fp8_f32 v104, v104, v105
	v_cvt_pk_fp8_f32 v108, v108, v109
	v_cvt_pk_fp8_f32 v96, v98, v99 op_sel:[0,0,1]
	v_cvt_pk_fp8_f32 v100, v102, v103 op_sel:[0,0,1]
	v_cvt_pk_fp8_f32 v104, v106, v107 op_sel:[0,0,1]
	v_cvt_pk_fp8_f32 v108, v110, v111 op_sel:[0,0,1]
	global_store_dword v[10:11], v96, off
	global_store_dword v[10:11], v100, off offset:256
	global_store_dword v[10:11], v104, off offset:512
	global_store_dword v[10:11], v108, off offset:768
	v_lshl_add_u64 v[10:11], v[10:11], 0, s[100:101]
	global_load_dwordx4 v[96:99], v[12:13], off
	global_load_dwordx4 v[100:103], v[12:13], off offset:1024
	global_load_dwordx4 v[104:107], v[12:13], off offset:2048
	global_load_dwordx4 v[108:111], v[12:13], off offset:3072
	v_lshl_add_u64 v[12:13], v[12:13], 0, s[98:99]
	v_cmp_lt_f32_e64 s[12:13], 0, v5
	v_div_scale_f32 v24, s[4:5], s64, s64, v5
	v_rcp_f32_e32 v25, v24
	v_div_scale_f32 v26, vcc, v5, s64, v5
	v_fma_f32 v27, -v24, v25, 1.0
	v_fmac_f32_e32 v25, v27, v25
	v_mul_f32_e32 v27, v26, v25
	v_fma_f32 v28, -v24, v27, v26
	v_fmac_f32_e32 v27, v28, v25
	v_fma_f32 v24, -v24, v27, v26
	v_div_fmas_f32 v24, v24, v25, v27
	v_div_fixup_f32 v29, v24, s64, v5
	v_cndmask_b32_e64 v29, 1.0, v29, s[12:13]
	v_add_u32_e32 v15, 0xa000, v14
	s_and_saveexec_b64 s[56:57], s[10:11]
	global_store_dword v15, v29, s[52:53]
	s_or_b64 exec, exec, s[56:57]
	v_div_scale_f32 v24, s[4:5], v5, v5, s64
	v_rcp_f32_e32 v25, v24
	v_div_scale_f32 v26, vcc, s64, v5, s64
	v_fma_f32 v27, -v24, v25, 1.0
	v_fmac_f32_e32 v25, v27, v25
	v_mul_f32_e32 v27, v26, v25
	v_fma_f32 v28, -v24, v27, v26
	v_fmac_f32_e32 v27, v28, v25
	v_fma_f32 v24, -v24, v27, v26
	v_div_fmas_f32 v24, v24, v25, v27
	v_div_fixup_f32 v30, v24, v5, s64
	v_cndmask_b32_e64 v30, 1.0, v30, s[12:13]
	v_mul_f32_e32 v112, v112, v30
	v_mul_f32_e32 v113, v113, v30
	v_mul_f32_e32 v114, v114, v30
	v_mul_f32_e32 v115, v115, v30
	v_mul_f32_e32 v116, v116, v30
	v_mul_f32_e32 v117, v117, v30
	v_mul_f32_e32 v118, v118, v30
	v_mul_f32_e32 v119, v119, v30
	v_mul_f32_e32 v120, v120, v30
	v_mul_f32_e32 v121, v121, v30
	v_mul_f32_e32 v122, v122, v30
	v_mul_f32_e32 v123, v123, v30
	v_mul_f32_e32 v124, v124, v30
	v_mul_f32_e32 v125, v125, v30
	v_mul_f32_e32 v126, v126, v30
	v_mul_f32_e32 v127, v127, v30
	v_cvt_pk_fp8_f32 v112, v112, v113
	v_cvt_pk_fp8_f32 v116, v116, v117
	v_cvt_pk_fp8_f32 v120, v120, v121
	v_cvt_pk_fp8_f32 v124, v124, v125
	v_cvt_pk_fp8_f32 v112, v114, v115 op_sel:[0,0,1]
	v_cvt_pk_fp8_f32 v116, v118, v119 op_sel:[0,0,1]
	v_cvt_pk_fp8_f32 v120, v122, v123 op_sel:[0,0,1]
	v_cvt_pk_fp8_f32 v124, v126, v127 op_sel:[0,0,1]
	global_store_dword v[10:11], v112, off
	global_store_dword v[10:11], v116, off offset:256
	global_store_dword v[10:11], v120, off offset:512
	global_store_dword v[10:11], v124, off offset:768
	v_lshl_add_u64 v[10:11], v[10:11], 0, s[100:101]
	global_load_dwordx4 v[112:115], v[12:13], off
	global_load_dwordx4 v[116:119], v[12:13], off offset:1024
	global_load_dwordx4 v[120:123], v[12:13], off offset:2048
	global_load_dwordx4 v[124:127], v[12:13], off offset:3072
	v_lshl_add_u64 v[12:13], v[12:13], 0, s[98:99]
	v_cmp_lt_f32_e64 s[12:13], 0, v6
	v_div_scale_f32 v24, s[4:5], s64, s64, v6
; DI void fp8_rows(const float* __restrict__ src, unsigned char* __restrict__ dst, float* __restrict__ rs, int nrows) {
;     ...
;     for (int i = 0; i < 4; ++i) {
;       v[i] = *(const float4*)(src + (size_t)row * 1024 + 4 * lane + 256 * i);
;       am = fmaxf(am, fmaxf(fmaxf(fabsf(v[i].x), fabsf(v[i].y)), fmaxf(fabsf(v[i].z), fabsf(v[i].w))));
;     }
;     am = fmaxf(am, __shfl_xor(am, 32)); am = fmaxf(am, __shfl_xor(am, 16)); am = fmaxf(am, __shfl_xor(am, 8));
;     am = fmaxf(am, __shfl_xor(am, 4)); am = fmaxf(am, __shfl_xor(am, 2)); am = fmaxf(am, __shfl_xor(am, 1));
;     const float sc = am > 0.f ? 440.f / am : 1.f;
;     if (lane == 0) rs[row] = am > 0.f ? am / 440.f : 1.f;
; #pragma unroll
;     for (int i = 0; i < 4; ++i) {
;       int pk = __builtin_amdgcn_cvt_pk_fp8_f32(v[i].x * sc, v[i].y * sc, 0, false);
;       pk = __builtin_amdgcn_cvt_pk_fp8_f32(v[i].z * sc, v[i].w * sc, pk, true);
;       *(int*)(dst + (size_t)row * 1024 + 4 * lane + 256 * i) = pk;
;     }
	v_rcp_f32_e32 v25, v24
	v_div_scale_f32 v26, vcc, v6, s64, v6
	v_fma_f32 v27, -v24, v25, 1.0
	v_fmac_f32_e32 v25, v27, v25
	v_mul_f32_e32 v27, v26, v25
	v_fma_f32 v28, -v24, v27, v26
	v_fmac_f32_e32 v27, v28, v25
	v_fma_f32 v24, -v24, v27, v26
	v_div_fmas_f32 v24, v24, v25, v27
	v_div_fixup_f32 v29, v24, s64, v6
	v_cndmask_b32_e64 v29, 1.0, v29, s[12:13]
	v_add_u32_e32 v15, 0xc000, v14
	s_and_saveexec_b64 s[56:57], s[10:11]
	global_store_dword v15, v29, s[52:53]
	s_or_b64 exec, exec, s[56:57]
	v_div_scale_f32 v24, s[4:5], v6, v6, s64
	v_rcp_f32_e32 v25, v24
	v_div_scale_f32 v26, vcc, s64, v6, s64
	v_fma_f32 v27, -v24, v25, 1.0
	v_fmac_f32_e32 v25, v27, v25
	v_mul_f32_e32 v27, v26, v25
	v_fma_f32 v28, -v24, v27, v26
	v_fmac_f32_e32 v27, v28, v25
	v_fma_f32 v24, -v24, v27, v26
	v_div_fmas_f32 v24, v24, v25, v27
	v_div_fixup_f32 v30, v24, v6, s64
	v_cndmask_b32_e64 v30, 1.0, v30, s[12:13]
	v_mul_f32_e32 v172, v172, v30
	v_mul_f32_e32 v173, v173, v30
	v_mul_f32_e32 v174, v174, v30
	v_mul_f32_e32 v175, v175, v30
	v_mul_f32_e32 v176, v176, v30
	v_mul_f32_e32 v177, v177, v30
	v_mul_f32_e32 v178, v178, v30
	v_mul_f32_e32 v179, v179, v30
	v_mul_f32_e32 v180, v180, v30
	v_mul_f32_e32 v181, v181, v30
	v_mul_f32_e32 v182, v182, v30
	v_mul_f32_e32 v183, v183, v30
	v_mul_f32_e32 v184, v184, v30
	v_mul_f32_e32 v185, v185, v30
	v_mul_f32_e32 v186, v186, v30
	v_mul_f32_e32 v187, v187, v30
	v_cvt_pk_fp8_f32 v172, v172, v173
	v_cvt_pk_fp8_f32 v176, v176, v177
	v_cvt_pk_fp8_f32 v180, v180, v181
	v_cvt_pk_fp8_f32 v184, v184, v185
	v_cvt_pk_fp8_f32 v172, v174, v175 op_sel:[0,0,1]
	v_cvt_pk_fp8_f32 v176, v178, v179 op_sel:[0,0,1]
	v_cvt_pk_fp8_f32 v180, v182, v183 op_sel:[0,0,1]
	v_cvt_pk_fp8_f32 v184, v186, v187 op_sel:[0,0,1]
	global_store_dword v[10:11], v172, off
	global_store_dword v[10:11], v176, off offset:256
	global_store_dword v[10:11], v180, off offset:512
	global_store_dword v[10:11], v184, off offset:768
	v_lshl_add_u64 v[10:11], v[10:11], 0, s[100:101]
	global_load_dwordx4 v[172:175], v[12:13], off
	global_load_dwordx4 v[176:179], v[12:13], off offset:1024
	global_load_dwordx4 v[180:183], v[12:13], off offset:2048
	global_load_dwordx4 v[184:187], v[12:13], off offset:3072
	v_lshl_add_u64 v[12:13], v[12:13], 0, s[98:99]
	v_cmp_lt_f32_e64 s[12:13], 0, v7
	v_div_scale_f32 v24, s[4:5], s64, s64, v7
	v_rcp_f32_e32 v25, v24
	v_div_scale_f32 v26, vcc, v7, s64, v7
	v_fma_f32 v27, -v24, v25, 1.0
	v_fmac_f32_e32 v25, v27, v25
	v_mul_f32_e32 v27, v26, v25
	v_fma_f32 v28, -v24, v27, v26
	v_fmac_f32_e32 v27, v28, v25
	v_fma_f32 v24, -v24, v27, v26
	v_div_fmas_f32 v24, v24, v25, v27
	v_div_fixup_f32 v29, v24, s64, v7
	v_cndmask_b32_e64 v29, 1.0, v29, s[12:13]
	v_add_u32_e32 v15, 0xe000, v14
	s_and_saveexec_b64 s[56:57], s[10:11]
	global_store_dword v15, v29, s[52:53]
	s_or_b64 exec, exec, s[56:57]
	v_div_scale_f32 v24, s[4:5], v7, v7, s64
	v_rcp_f32_e32 v25, v24
	v_div_scale_f32 v26, vcc, s64, v7, s64
	v_fma_f32 v27, -v24, v25, 1.0
	v_fmac_f32_e32 v25, v27, v25
	v_mul_f32_e32 v27, v26, v25
	v_fma_f32 v28, -v24, v27, v26
	v_fmac_f32_e32 v27, v28, v25
	v_fma_f32 v24, -v24, v27, v26
	v_div_fmas_f32 v24, v24, v25, v27
	v_div_fixup_f32 v30, v24, v7, s64
	v_cndmask_b32_e64 v30, 1.0, v30, s[12:13]
	v_mul_f32_e32 v188, v188, v30
	v_mul_f32_e32 v189, v189, v30
	v_mul_f32_e32 v190, v190, v30
	v_mul_f32_e32 v191, v191, v30
	v_mul_f32_e32 v192, v192, v30
	v_mul_f32_e32 v193, v193, v30
	v_mul_f32_e32 v194, v194, v30
	v_mul_f32_e32 v195, v195, v30
	v_mul_f32_e32 v196, v196, v30
	v_mul_f32_e32 v197, v197, v30
	v_mul_f32_e32 v198, v198, v30
	v_mul_f32_e32 v199, v199, v30
	v_mul_f32_e32 v200, v200, v30
	v_mul_f32_e32 v201, v201, v30
	v_mul_f32_e32 v202, v202, v30
	v_mul_f32_e32 v203, v203, v30
	v_cvt_pk_fp8_f32 v188, v188, v189
	v_cvt_pk_fp8_f32 v192, v192, v193
	v_cvt_pk_fp8_f32 v196, v196, v197
	v_cvt_pk_fp8_f32 v200, v200, v201
	v_cvt_pk_fp8_f32 v188, v190, v191 op_sel:[0,0,1]
	v_cvt_pk_fp8_f32 v192, v194, v195 op_sel:[0,0,1]
	v_cvt_pk_fp8_f32 v196, v198, v199 op_sel:[0,0,1]
	v_cvt_pk_fp8_f32 v200, v202, v203 op_sel:[0,0,1]
	global_store_dword v[10:11], v188, off
	global_store_dword v[10:11], v192, off offset:256
	global_store_dword v[10:11], v196, off offset:512
	global_store_dword v[10:11], v200, off offset:768
	global_load_dwordx4 v[188:191], v[12:13], off
	global_load_dwordx4 v[192:195], v[12:13], off offset:1024
	global_load_dwordx4 v[196:199], v[12:13], off offset:2048
	global_load_dwordx4 v[200:203], v[12:13], off offset:3072
	v_lshlrev_b32_e32 v10, 10, v226
	v_mov_b32_e32 v11, 0
	v_lshl_add_u64 v[10:11], v[136:137], 0, v[10:11]
	s_waitcnt vmcnt(63)
	v_max3_f32 v0, |v32|, |v33|, 0
	v_max3_f32 v0, |v34|, |v35|, v0
	v_max3_f32 v0, |v36|, |v37|, v0
	v_max3_f32 v0, |v38|, |v39|, v0
	v_max3_f32 v0, |v40|, |v41|, v0
	v_max3_f32 v0, |v42|, |v43|, v0
	v_max3_f32 v0, |v44|, |v45|, v0
	v_max3_f32 v0, |v46|, |v47|, v0
	s_nop 1
	v_max_f32_dpp v0, v0, v0 quad_perm:[1,0,3,2] row_mask:0xf bank_mask:0xf
	s_nop 1
	v_max_f32_dpp v0, v0, v0 quad_perm:[2,3,0,1] row_mask:0xf bank_mask:0xf
	s_nop 1
	v_max_f32_dpp v0, v0, v0 row_half_mirror row_mask:0xf bank_mask:0xf
	s_nop 1
	v_max_f32_dpp v0, v0, v0 row_mirror row_mask:0xf bank_mask:0xf
	v_mov_b32_e32 v15, v0
	s_nop 1
	v_permlane16_swap_b32_e32 v0, v15
	v_max_f32_e32 v0, v0, v15
	v_mov_b32_e32 v15, v0
	s_nop 1
	v_permlane32_swap_b32_e32 v0, v15
	v_max_f32_e32 v0, v0, v15
	s_waitcnt vmcnt(54)
; DI void fp8_rows(const float* __restrict__ src, unsigned char* __restrict__ dst, float* __restrict__ rs, int nrows) {
;     ...
;     for (int i = 0; i < 4; ++i) {
;       v[i] = *(const float4*)(src + (size_t)row * 1024 + 4 * lane + 256 * i);
;       am = fmaxf(am, fmaxf(fmaxf(fabsf(v[i].x), fabsf(v[i].y)), fmaxf(fabsf(v[i].z), fabsf(v[i].w))));
;     }
;     am = fmaxf(am, __shfl_xor(am, 32)); am = fmaxf(am, __shfl_xor(am, 16)); am = fmaxf(am, __shfl_xor(am, 8));
;     am = fmaxf(am, __shfl_xor(am, 4)); am = fmaxf(am, __shfl_xor(am, 2)); am = fmaxf(am, __shfl_xor(am, 1));
	v_max3_f32 v1, |v48|, |v49|, 0
	v_max3_f32 v1, |v50|, |v51|, v1
	v_max3_f32 v1, |v52|, |v53|, v1
	v_max3_f32 v1, |v54|, |v55|, v1
	v_max3_f32 v1, |v56|, |v57|, v1
	v_max3_f32 v1, |v58|, |v59|, v1
	v_max3_f32 v1, |v60|, |v61|, v1
	v_max3_f32 v1, |v62|, |v63|, v1
	s_nop 1
	v_max_f32_dpp v1, v1, v1 quad_perm:[1,0,3,2] row_mask:0xf bank_mask:0xf
	s_nop 1
	v_max_f32_dpp v1, v1, v1 quad_perm:[2,3,0,1] row_mask:0xf bank_mask:0xf
	s_nop 1
	v_max_f32_dpp v1, v1, v1 row_half_mirror row_mask:0xf bank_mask:0xf
	s_nop 1
	v_max_f32_dpp v1, v1, v1 row_mirror row_mask:0xf bank_mask:0xf
	v_mov_b32_e32 v15, v1
	s_nop 1
	v_permlane16_swap_b32_e32 v1, v15
	v_max_f32_e32 v1, v1, v15
	v_mov_b32_e32 v15, v1
	s_nop 1
	v_permlane32_swap_b32_e32 v1, v15
	v_max_f32_e32 v1, v1, v15
	s_waitcnt vmcnt(45)
	v_max3_f32 v2, |v64|, |v65|, 0
	v_max3_f32 v2, |v66|, |v67|, v2
	v_max3_f32 v2, |v68|, |v69|, v2
	v_max3_f32 v2, |v70|, |v71|, v2
	v_max3_f32 v2, |v72|, |v73|, v2
	v_max3_f32 v2, |v74|, |v75|, v2
	v_max3_f32 v2, |v76|, |v77|, v2
	v_max3_f32 v2, |v78|, |v79|, v2
	s_nop 1
	v_max_f32_dpp v2, v2, v2 quad_perm:[1,0,3,2] row_mask:0xf bank_mask:0xf
	s_nop 1
	v_max_f32_dpp v2, v2, v2 quad_perm:[2,3,0,1] row_mask:0xf bank_mask:0xf
	s_nop 1
	v_max_f32_dpp v2, v2, v2 row_half_mirror row_mask:0xf bank_mask:0xf
	s_nop 1
	v_max_f32_dpp v2, v2, v2 row_mirror row_mask:0xf bank_mask:0xf
	v_mov_b32_e32 v15, v2
	s_nop 1
	v_permlane16_swap_b32_e32 v2, v15
	v_max_f32_e32 v2, v2, v15
	v_mov_b32_e32 v15, v2
	s_nop 1
	v_permlane32_swap_b32_e32 v2, v15
	v_max_f32_e32 v2, v2, v15
	s_waitcnt vmcnt(36)
	v_max3_f32 v3, |v80|, |v81|, 0
	v_max3_f32 v3, |v82|, |v83|, v3
	v_max3_f32 v3, |v84|, |v85|, v3
	v_max3_f32 v3, |v86|, |v87|, v3
	v_max3_f32 v3, |v88|, |v89|, v3
	v_max3_f32 v3, |v90|, |v91|, v3
	v_max3_f32 v3, |v92|, |v93|, v3
	v_max3_f32 v3, |v94|, |v95|, v3
	s_nop 1
	v_max_f32_dpp v3, v3, v3 quad_perm:[1,0,3,2] row_mask:0xf bank_mask:0xf
	s_nop 1
	v_max_f32_dpp v3, v3, v3 quad_perm:[2,3,0,1] row_mask:0xf bank_mask:0xf
	s_nop 1
	v_max_f32_dpp v3, v3, v3 row_half_mirror row_mask:0xf bank_mask:0xf
	s_nop 1
	v_max_f32_dpp v3, v3, v3 row_mirror row_mask:0xf bank_mask:0xf
	v_mov_b32_e32 v15, v3
	s_nop 1
	v_permlane16_swap_b32_e32 v3, v15
	v_max_f32_e32 v3, v3, v15
	v_mov_b32_e32 v15, v3
	s_nop 1
	v_permlane32_swap_b32_e32 v3, v15
	v_max_f32_e32 v3, v3, v15
	s_waitcnt vmcnt(27)
	v_max3_f32 v4, |v96|, |v97|, 0
	v_max3_f32 v4, |v98|, |v99|, v4
	v_max3_f32 v4, |v100|, |v101|, v4
	v_max3_f32 v4, |v102|, |v103|, v4
	v_max3_f32 v4, |v104|, |v105|, v4
	v_max3_f32 v4, |v106|, |v107|, v4
	v_max3_f32 v4, |v108|, |v109|, v4
	v_max3_f32 v4, |v110|, |v111|, v4
	s_nop 1
	v_max_f32_dpp v4, v4, v4 quad_perm:[1,0,3,2] row_mask:0xf bank_mask:0xf
	s_nop 1
	v_max_f32_dpp v4, v4, v4 quad_perm:[2,3,0,1] row_mask:0xf bank_mask:0xf
	s_nop 1
	v_max_f32_dpp v4, v4, v4 row_half_mirror row_mask:0xf bank_mask:0xf
	s_nop 1
	v_max_f32_dpp v4, v4, v4 row_mirror row_mask:0xf bank_mask:0xf
	v_mov_b32_e32 v15, v4
	s_nop 1
	v_permlane16_swap_b32_e32 v4, v15
	v_max_f32_e32 v4, v4, v15
	v_mov_b32_e32 v15, v4
	s_nop 1
	v_permlane32_swap_b32_e32 v4, v15
	v_max_f32_e32 v4, v4, v15
	s_waitcnt vmcnt(18)
	v_max3_f32 v5, |v112|, |v113|, 0
	v_max3_f32 v5, |v114|, |v115|, v5
	v_max3_f32 v5, |v116|, |v117|, v5
	v_max3_f32 v5, |v118|, |v119|, v5
	v_max3_f32 v5, |v120|, |v121|, v5
	v_max3_f32 v5, |v122|, |v123|, v5
	v_max3_f32 v5, |v124|, |v125|, v5
	v_max3_f32 v5, |v126|, |v127|, v5
	s_nop 1
	v_max_f32_dpp v5, v5, v5 quad_perm:[1,0,3,2] row_mask:0xf bank_mask:0xf
	s_nop 1
	v_max_f32_dpp v5, v5, v5 quad_perm:[2,3,0,1] row_mask:0xf bank_mask:0xf
	s_nop 1
	v_max_f32_dpp v5, v5, v5 row_half_mirror row_mask:0xf bank_mask:0xf
	s_nop 1
	v_max_f32_dpp v5, v5, v5 row_mirror row_mask:0xf bank_mask:0xf
	v_mov_b32_e32 v15, v5
	s_nop 1
	v_permlane16_swap_b32_e32 v5, v15
	v_max_f32_e32 v5, v5, v15
	v_mov_b32_e32 v15, v5
	s_nop 1
	v_permlane32_swap_b32_e32 v5, v15
	v_max_f32_e32 v5, v5, v15
	s_waitcnt vmcnt(9)
	v_max3_f32 v6, |v172|, |v173|, 0
	v_max3_f32 v6, |v174|, |v175|, v6
	v_max3_f32 v6, |v176|, |v177|, v6
	v_max3_f32 v6, |v178|, |v179|, v6
	v_max3_f32 v6, |v180|, |v181|, v6
	v_max3_f32 v6, |v182|, |v183|, v6
	v_max3_f32 v6, |v184|, |v185|, v6
	v_max3_f32 v6, |v186|, |v187|, v6
	s_nop 1
	v_max_f32_dpp v6, v6, v6 quad_perm:[1,0,3,2] row_mask:0xf bank_mask:0xf
	s_nop 1
	v_max_f32_dpp v6, v6, v6 quad_perm:[2,3,0,1] row_mask:0xf bank_mask:0xf
	s_nop 1
	v_max_f32_dpp v6, v6, v6 row_half_mirror row_mask:0xf bank_mask:0xf
	s_nop 1
	v_max_f32_dpp v6, v6, v6 row_mirror row_mask:0xf bank_mask:0xf
	v_mov_b32_e32 v15, v6
	s_nop 1
	v_permlane16_swap_b32_e32 v6, v15
	v_max_f32_e32 v6, v6, v15
	v_mov_b32_e32 v15, v6
	s_nop 1
	v_permlane32_swap_b32_e32 v6, v15
	v_max_f32_e32 v6, v6, v15
	s_waitcnt vmcnt(0)
; DI void fp8_rows(const float* __restrict__ src, unsigned char* __restrict__ dst, float* __restrict__ rs, int nrows) {
;     ...
;     for (int i = 0; i < 4; ++i) {
;       v[i] = *(const float4*)(src + (size_t)row * 1024 + 4 * lane + 256 * i);
;       am = fmaxf(am, fmaxf(fmaxf(fabsf(v[i].x), fabsf(v[i].y)), fmaxf(fabsf(v[i].z), fabsf(v[i].w))));
;     }
;     am = fmaxf(am, __shfl_xor(am, 32)); am = fmaxf(am, __shfl_xor(am, 16)); am = fmaxf(am, __shfl_xor(am, 8));
;     am = fmaxf(am, __shfl_xor(am, 4)); am = fmaxf(am, __shfl_xor(am, 2)); am = fmaxf(am, __shfl_xor(am, 1));
;     const float sc = am > 0.f ? 440.f / am : 1.f;
;     if (lane == 0) rs[row] = am > 0.f ? am / 440.f : 1.f;
; #pragma unroll
;     for (int i = 0; i < 4; ++i) {
;       int pk = __builtin_amdgcn_cvt_pk_fp8_f32(v[i].x * sc, v[i].y * sc, 0, false);
;       pk = __builtin_amdgcn_cvt_pk_fp8_f32(v[i].z * sc, v[i].w * sc, pk, true);
;       *(int*)(dst + (size_t)row * 1024 + 4 * lane + 256 * i) = pk;
;     }
	v_max3_f32 v7, |v188|, |v189|, 0
	v_max3_f32 v7, |v190|, |v191|, v7
	v_max3_f32 v7, |v192|, |v193|, v7
	v_max3_f32 v7, |v194|, |v195|, v7
	v_max3_f32 v7, |v196|, |v197|, v7
	v_max3_f32 v7, |v198|, |v199|, v7
	v_max3_f32 v7, |v200|, |v201|, v7
	v_max3_f32 v7, |v202|, |v203|, v7
	s_nop 1
	v_max_f32_dpp v7, v7, v7 quad_perm:[1,0,3,2] row_mask:0xf bank_mask:0xf
	s_nop 1
	v_max_f32_dpp v7, v7, v7 quad_perm:[2,3,0,1] row_mask:0xf bank_mask:0xf
	s_nop 1
	v_max_f32_dpp v7, v7, v7 row_half_mirror row_mask:0xf bank_mask:0xf
	s_nop 1
	v_max_f32_dpp v7, v7, v7 row_mirror row_mask:0xf bank_mask:0xf
	v_mov_b32_e32 v15, v7
	s_nop 1
	v_permlane16_swap_b32_e32 v7, v15
	v_max_f32_e32 v7, v7, v15
	v_mov_b32_e32 v15, v7
	s_nop 1
	v_permlane32_swap_b32_e32 v7, v15
	v_max_f32_e32 v7, v7, v15
	v_cmp_lt_f32_e64 s[12:13], 0, v0
	v_div_scale_f32 v24, s[4:5], s64, s64, v0
	v_rcp_f32_e32 v25, v24
	v_div_scale_f32 v26, vcc, v0, s64, v0
	v_fma_f32 v27, -v24, v25, 1.0
	v_fmac_f32_e32 v25, v27, v25
	v_mul_f32_e32 v27, v26, v25
	v_fma_f32 v28, -v24, v27, v26
	v_fmac_f32_e32 v27, v28, v25
	v_fma_f32 v24, -v24, v27, v26
	v_div_fmas_f32 v24, v24, v25, v27
	v_div_fixup_f32 v29, v24, s64, v0
	v_cndmask_b32_e64 v29, 1.0, v29, s[12:13]
	v_mov_b32_e32 v15, v14
	s_and_saveexec_b64 s[56:57], s[10:11]
	global_store_dword v15, v29, s[16:17]
	s_or_b64 exec, exec, s[56:57]
	v_div_scale_f32 v24, s[4:5], v0, v0, s64
	v_rcp_f32_e32 v25, v24
	v_div_scale_f32 v26, vcc, s64, v0, s64
	v_fma_f32 v27, -v24, v25, 1.0
	v_fmac_f32_e32 v25, v27, v25
	v_mul_f32_e32 v27, v26, v25
	v_fma_f32 v28, -v24, v27, v26
	v_fmac_f32_e32 v27, v28, v25
	v_fma_f32 v24, -v24, v27, v26
	v_div_fmas_f32 v24, v24, v25, v27
	v_div_fixup_f32 v30, v24, v0, s64
	v_cndmask_b32_e64 v30, 1.0, v30, s[12:13]
	v_mul_f32_e32 v32, v32, v30
	v_mul_f32_e32 v33, v33, v30
	v_mul_f32_e32 v34, v34, v30
	v_mul_f32_e32 v35, v35, v30
	v_mul_f32_e32 v36, v36, v30
	v_mul_f32_e32 v37, v37, v30
	v_mul_f32_e32 v38, v38, v30
	v_mul_f32_e32 v39, v39, v30
	v_mul_f32_e32 v40, v40, v30
	v_mul_f32_e32 v41, v41, v30
	v_mul_f32_e32 v42, v42, v30
	v_mul_f32_e32 v43, v43, v30
	v_mul_f32_e32 v44, v44, v30
	v_mul_f32_e32 v45, v45, v30
	v_mul_f32_e32 v46, v46, v30
	v_mul_f32_e32 v47, v47, v30
	v_cvt_pk_fp8_f32 v32, v32, v33
	v_cvt_pk_fp8_f32 v36, v36, v37
	v_cvt_pk_fp8_f32 v40, v40, v41
	v_cvt_pk_fp8_f32 v44, v44, v45
	v_cvt_pk_fp8_f32 v32, v34, v35 op_sel:[0,0,1]
	v_cvt_pk_fp8_f32 v36, v38, v39 op_sel:[0,0,1]
	v_cvt_pk_fp8_f32 v40, v42, v43 op_sel:[0,0,1]
	v_cvt_pk_fp8_f32 v44, v46, v47 op_sel:[0,0,1]
	global_store_dword v[10:11], v32, off
	global_store_dword v[10:11], v36, off offset:256
	global_store_dword v[10:11], v40, off offset:512
	global_store_dword v[10:11], v44, off offset:768
	v_lshl_add_u64 v[10:11], v[10:11], 0, s[100:101]
	v_cmp_lt_f32_e64 s[12:13], 0, v1
	v_div_scale_f32 v24, s[4:5], s64, s64, v1
	v_rcp_f32_e32 v25, v24
	v_div_scale_f32 v26, vcc, v1, s64, v1
	v_fma_f32 v27, -v24, v25, 1.0
	v_fmac_f32_e32 v25, v27, v25
	v_mul_f32_e32 v27, v26, v25
	v_fma_f32 v28, -v24, v27, v26
	v_fmac_f32_e32 v27, v28, v25
	v_fma_f32 v24, -v24, v27, v26
	v_div_fmas_f32 v24, v24, v25, v27
	v_div_fixup_f32 v29, v24, s64, v1
	v_cndmask_b32_e64 v29, 1.0, v29, s[12:13]
	v_add_u32_e32 v15, 0x2000, v14
	s_and_saveexec_b64 s[56:57], s[10:11]
	global_store_dword v15, v29, s[16:17]
	s_or_b64 exec, exec, s[56:57]
	v_div_scale_f32 v24, s[4:5], v1, v1, s64
	v_rcp_f32_e32 v25, v24
	v_div_scale_f32 v26, vcc, s64, v1, s64
	v_fma_f32 v27, -v24, v25, 1.0
	v_fmac_f32_e32 v25, v27, v25
	v_mul_f32_e32 v27, v26, v25
	v_fma_f32 v28, -v24, v27, v26
	v_fmac_f32_e32 v27, v28, v25
	v_fma_f32 v24, -v24, v27, v26
	v_div_fmas_f32 v24, v24, v25, v27
	v_div_fixup_f32 v30, v24, v1, s64
	v_cndmask_b32_e64 v30, 1.0, v30, s[12:13]
	v_mul_f32_e32 v48, v48, v30
	v_mul_f32_e32 v49, v49, v30
	v_mul_f32_e32 v50, v50, v30
	v_mul_f32_e32 v51, v51, v30
	v_mul_f32_e32 v52, v52, v30
	v_mul_f32_e32 v53, v53, v30
	v_mul_f32_e32 v54, v54, v30
	v_mul_f32_e32 v55, v55, v30
	v_mul_f32_e32 v56, v56, v30
	v_mul_f32_e32 v57, v57, v30
	v_mul_f32_e32 v58, v58, v30
	v_mul_f32_e32 v59, v59, v30
	v_mul_f32_e32 v60, v60, v30
	v_mul_f32_e32 v61, v61, v30
	v_mul_f32_e32 v62, v62, v30
	v_mul_f32_e32 v63, v63, v30
	v_cvt_pk_fp8_f32 v48, v48, v49
	v_cvt_pk_fp8_f32 v52, v52, v53
	v_cvt_pk_fp8_f32 v56, v56, v57
	v_cvt_pk_fp8_f32 v60, v60, v61
	v_cvt_pk_fp8_f32 v48, v50, v51 op_sel:[0,0,1]
	v_cvt_pk_fp8_f32 v52, v54, v55 op_sel:[0,0,1]
	v_cvt_pk_fp8_f32 v56, v58, v59 op_sel:[0,0,1]
	v_cvt_pk_fp8_f32 v60, v62, v63 op_sel:[0,0,1]
	global_store_dword v[10:11], v48, off
	global_store_dword v[10:11], v52, off offset:256
	global_store_dword v[10:11], v56, off offset:512
	global_store_dword v[10:11], v60, off offset:768
	v_lshl_add_u64 v[10:11], v[10:11], 0, s[100:101]
	v_cmp_lt_f32_e64 s[12:13], 0, v2
	v_div_scale_f32 v24, s[4:5], s64, s64, v2
	v_rcp_f32_e32 v25, v24
	v_div_scale_f32 v26, vcc, v2, s64, v2
	v_fma_f32 v27, -v24, v25, 1.0
	v_fmac_f32_e32 v25, v27, v25
	v_mul_f32_e32 v27, v26, v25
	v_fma_f32 v28, -v24, v27, v26
	v_fmac_f32_e32 v27, v28, v25
	v_fma_f32 v24, -v24, v27, v26
	v_div_fmas_f32 v24, v24, v25, v27
	v_div_fixup_f32 v29, v24, s64, v2
	v_cndmask_b32_e64 v29, 1.0, v29, s[12:13]
	v_add_u32_e32 v15, 0x4000, v14
	s_and_saveexec_b64 s[56:57], s[10:11]
	global_store_dword v15, v29, s[16:17]
	s_or_b64 exec, exec, s[56:57]
	v_div_scale_f32 v24, s[4:5], v2, v2, s64
	v_rcp_f32_e32 v25, v24
	v_div_scale_f32 v26, vcc, s64, v2, s64
	v_fma_f32 v27, -v24, v25, 1.0
	v_fmac_f32_e32 v25, v27, v25
	v_mul_f32_e32 v27, v26, v25
	v_fma_f32 v28, -v24, v27, v26
	v_fmac_f32_e32 v27, v28, v25
	v_fma_f32 v24, -v24, v27, v26
; DI void fp8_rows(const float* __restrict__ src, unsigned char* __restrict__ dst, float* __restrict__ rs, int nrows) {
;     ...
;     const float sc = am > 0.f ? 440.f / am : 1.f;
;     if (lane == 0) rs[row] = am > 0.f ? am / 440.f : 1.f;
; #pragma unroll
;     for (int i = 0; i < 4; ++i) {
;       int pk = __builtin_amdgcn_cvt_pk_fp8_f32(v[i].x * sc, v[i].y * sc, 0, false);
;       pk = __builtin_amdgcn_cvt_pk_fp8_f32(v[i].z * sc, v[i].w * sc, pk, true);
;       *(int*)(dst + (size_t)row * 1024 + 4 * lane + 256 * i) = pk;
;     }
	v_div_fmas_f32 v24, v24, v25, v27
	v_div_fixup_f32 v30, v24, v2, s64
	v_cndmask_b32_e64 v30, 1.0, v30, s[12:13]
	v_mul_f32_e32 v64, v64, v30
	v_mul_f32_e32 v65, v65, v30
	v_mul_f32_e32 v66, v66, v30
	v_mul_f32_e32 v67, v67, v30
	v_mul_f32_e32 v68, v68, v30
	v_mul_f32_e32 v69, v69, v30
	v_mul_f32_e32 v70, v70, v30
	v_mul_f32_e32 v71, v71, v30
	v_mul_f32_e32 v72, v72, v30
	v_mul_f32_e32 v73, v73, v30
	v_mul_f32_e32 v74, v74, v30
	v_mul_f32_e32 v75, v75, v30
	v_mul_f32_e32 v76, v76, v30
	v_mul_f32_e32 v77, v77, v30
	v_mul_f32_e32 v78, v78, v30
	v_mul_f32_e32 v79, v79, v30
	v_cvt_pk_fp8_f32 v64, v64, v65
	v_cvt_pk_fp8_f32 v68, v68, v69
	v_cvt_pk_fp8_f32 v72, v72, v73
	v_cvt_pk_fp8_f32 v76, v76, v77
	v_cvt_pk_fp8_f32 v64, v66, v67 op_sel:[0,0,1]
	v_cvt_pk_fp8_f32 v68, v70, v71 op_sel:[0,0,1]
	v_cvt_pk_fp8_f32 v72, v74, v75 op_sel:[0,0,1]
	v_cvt_pk_fp8_f32 v76, v78, v79 op_sel:[0,0,1]
	global_store_dword v[10:11], v64, off
	global_store_dword v[10:11], v68, off offset:256
	global_store_dword v[10:11], v72, off offset:512
	global_store_dword v[10:11], v76, off offset:768
	v_lshl_add_u64 v[10:11], v[10:11], 0, s[100:101]
	v_cmp_lt_f32_e64 s[12:13], 0, v3
	v_div_scale_f32 v24, s[4:5], s64, s64, v3
	v_rcp_f32_e32 v25, v24
	v_div_scale_f32 v26, vcc, v3, s64, v3
	v_fma_f32 v27, -v24, v25, 1.0
	v_fmac_f32_e32 v25, v27, v25
	v_mul_f32_e32 v27, v26, v25
	v_fma_f32 v28, -v24, v27, v26
	v_fmac_f32_e32 v27, v28, v25
	v_fma_f32 v24, -v24, v27, v26
	v_div_fmas_f32 v24, v24, v25, v27
	v_div_fixup_f32 v29, v24, s64, v3
	v_cndmask_b32_e64 v29, 1.0, v29, s[12:13]
	v_add_u32_e32 v15, 0x6000, v14
	s_and_saveexec_b64 s[56:57], s[10:11]
	global_store_dword v15, v29, s[16:17]
	s_or_b64 exec, exec, s[56:57]
	v_div_scale_f32 v24, s[4:5], v3, v3, s64
	v_rcp_f32_e32 v25, v24
	v_div_scale_f32 v26, vcc, s64, v3, s64
	v_fma_f32 v27, -v24, v25, 1.0
	v_fmac_f32_e32 v25, v27, v25
	v_mul_f32_e32 v27, v26, v25
	v_fma_f32 v28, -v24, v27, v26
	v_fmac_f32_e32 v27, v28, v25
	v_fma_f32 v24, -v24, v27, v26
	v_div_fmas_f32 v24, v24, v25, v27
	v_div_fixup_f32 v30, v24, v3, s64
	v_cndmask_b32_e64 v30, 1.0, v30, s[12:13]
	v_mul_f32_e32 v80, v80, v30
	v_mul_f32_e32 v81, v81, v30
	v_mul_f32_e32 v82, v82, v30
	v_mul_f32_e32 v83, v83, v30
	v_mul_f32_e32 v84, v84, v30
	v_mul_f32_e32 v85, v85, v30
	v_mul_f32_e32 v86, v86, v30
	v_mul_f32_e32 v87, v87, v30
	v_mul_f32_e32 v88, v88, v30
	v_mul_f32_e32 v89, v89, v30
	v_mul_f32_e32 v90, v90, v30
	v_mul_f32_e32 v91, v91, v30
	v_mul_f32_e32 v92, v92, v30
	v_mul_f32_e32 v93, v93, v30
	v_mul_f32_e32 v94, v94, v30
	v_mul_f32_e32 v95, v95, v30
	v_cvt_pk_fp8_f32 v80, v80, v81
	v_cvt_pk_fp8_f32 v84, v84, v85
	v_cvt_pk_fp8_f32 v88, v88, v89
	v_cvt_pk_fp8_f32 v92, v92, v93
	v_cvt_pk_fp8_f32 v80, v82, v83 op_sel:[0,0,1]
	v_cvt_pk_fp8_f32 v84, v86, v87 op_sel:[0,0,1]
	v_cvt_pk_fp8_f32 v88, v90, v91 op_sel:[0,0,1]
	v_cvt_pk_fp8_f32 v92, v94, v95 op_sel:[0,0,1]
	global_store_dword v[10:11], v80, off
	global_store_dword v[10:11], v84, off offset:256
	global_store_dword v[10:11], v88, off offset:512
	global_store_dword v[10:11], v92, off offset:768
	v_lshl_add_u64 v[10:11], v[10:11], 0, s[100:101]
	v_cmp_lt_f32_e64 s[12:13], 0, v4
	v_div_scale_f32 v24, s[4:5], s64, s64, v4
	v_rcp_f32_e32 v25, v24
	v_div_scale_f32 v26, vcc, v4, s64, v4
	v_fma_f32 v27, -v24, v25, 1.0
	v_fmac_f32_e32 v25, v27, v25
	v_mul_f32_e32 v27, v26, v25
	v_fma_f32 v28, -v24, v27, v26
	v_fmac_f32_e32 v27, v28, v25
	v_fma_f32 v24, -v24, v27, v26
	v_div_fmas_f32 v24, v24, v25, v27
	v_div_fixup_f32 v29, v24, s64, v4
	v_cndmask_b32_e64 v29, 1.0, v29, s[12:13]
	v_add_u32_e32 v15, 0x8000, v14
	s_and_saveexec_b64 s[56:57], s[10:11]
	global_store_dword v15, v29, s[16:17]
	s_or_b64 exec, exec, s[56:57]
	v_div_scale_f32 v24, s[4:5], v4, v4, s64
	v_rcp_f32_e32 v25, v24
	v_div_scale_f32 v26, vcc, s64, v4, s64
	v_fma_f32 v27, -v24, v25, 1.0
	v_fmac_f32_e32 v25, v27, v25
	v_mul_f32_e32 v27, v26, v25
	v_fma_f32 v28, -v24, v27, v26
	v_fmac_f32_e32 v27, v28, v25
	v_fma_f32 v24, -v24, v27, v26
	v_div_fmas_f32 v24, v24, v25, v27
	v_div_fixup_f32 v30, v24, v4, s64
	v_cndmask_b32_e64 v30, 1.0, v30, s[12:13]
	v_mul_f32_e32 v96, v96, v30
	v_mul_f32_e32 v97, v97, v30
	v_mul_f32_e32 v98, v98, v30
	v_mul_f32_e32 v99, v99, v30
	v_mul_f32_e32 v100, v100, v30
	v_mul_f32_e32 v101, v101, v30
	v_mul_f32_e32 v102, v102, v30
	v_mul_f32_e32 v103, v103, v30
	v_mul_f32_e32 v104, v104, v30
	v_mul_f32_e32 v105, v105, v30
	v_mul_f32_e32 v106, v106, v30
	v_mul_f32_e32 v107, v107, v30
	v_mul_f32_e32 v108, v108, v30
	v_mul_f32_e32 v109, v109, v30
	v_mul_f32_e32 v110, v110, v30
	v_mul_f32_e32 v111, v111, v30
	v_cvt_pk_fp8_f32 v96, v96, v97
	v_cvt_pk_fp8_f32 v100, v100, v101
	v_cvt_pk_fp8_f32 v104, v104, v105
	v_cvt_pk_fp8_f32 v108, v108, v109
	v_cvt_pk_fp8_f32 v96, v98, v99 op_sel:[0,0,1]
	v_cvt_pk_fp8_f32 v100, v102, v103 op_sel:[0,0,1]
	v_cvt_pk_fp8_f32 v104, v106, v107 op_sel:[0,0,1]
	v_cvt_pk_fp8_f32 v108, v110, v111 op_sel:[0,0,1]
	global_store_dword v[10:11], v96, off
	global_store_dword v[10:11], v100, off offset:256
	global_store_dword v[10:11], v104, off offset:512
	global_store_dword v[10:11], v108, off offset:768
	v_lshl_add_u64 v[10:11], v[10:11], 0, s[100:101]
	v_cmp_lt_f32_e64 s[12:13], 0, v5
	v_div_scale_f32 v24, s[4:5], s64, s64, v5
	v_rcp_f32_e32 v25, v24
	v_div_scale_f32 v26, vcc, v5, s64, v5
	v_fma_f32 v27, -v24, v25, 1.0
	v_fmac_f32_e32 v25, v27, v25
	v_mul_f32_e32 v27, v26, v25
	v_fma_f32 v28, -v24, v27, v26
	v_fmac_f32_e32 v27, v28, v25
	v_fma_f32 v24, -v24, v27, v26
	v_div_fmas_f32 v24, v24, v25, v27
	v_div_fixup_f32 v29, v24, s64, v5
	v_cndmask_b32_e64 v29, 1.0, v29, s[12:13]
	v_add_u32_e32 v15, 0xa000, v14
; DI void fp8_rows(const float* __restrict__ src, unsigned char* __restrict__ dst, float* __restrict__ rs, int nrows) {
;     ...
;     const float sc = am > 0.f ? 440.f / am : 1.f;
;     if (lane == 0) rs[row] = am > 0.f ? am / 440.f : 1.f;
; #pragma unroll
;     for (int i = 0; i < 4; ++i) {
;       int pk = __builtin_amdgcn_cvt_pk_fp8_f32(v[i].x * sc, v[i].y * sc, 0, false);
;       pk = __builtin_amdgcn_cvt_pk_fp8_f32(v[i].z * sc, v[i].w * sc, pk, true);
;       *(int*)(dst + (size_t)row * 1024 + 4 * lane + 256 * i) = pk;
;     }
	s_and_saveexec_b64 s[56:57], s[10:11]
	global_store_dword v15, v29, s[16:17]
	s_or_b64 exec, exec, s[56:57]
	v_div_scale_f32 v24, s[4:5], v5, v5, s64
	v_rcp_f32_e32 v25, v24
	v_div_scale_f32 v26, vcc, s64, v5, s64
	v_fma_f32 v27, -v24, v25, 1.0
	v_fmac_f32_e32 v25, v27, v25
	v_mul_f32_e32 v27, v26, v25
	v_fma_f32 v28, -v24, v27, v26
	v_fmac_f32_e32 v27, v28, v25
	v_fma_f32 v24, -v24, v27, v26
	v_div_fmas_f32 v24, v24, v25, v27
	v_div_fixup_f32 v30, v24, v5, s64
	v_cndmask_b32_e64 v30, 1.0, v30, s[12:13]
	v_mul_f32_e32 v112, v112, v30
	v_mul_f32_e32 v113, v113, v30
	v_mul_f32_e32 v114, v114, v30
	v_mul_f32_e32 v115, v115, v30
	v_mul_f32_e32 v116, v116, v30
	v_mul_f32_e32 v117, v117, v30
	v_mul_f32_e32 v118, v118, v30
	v_mul_f32_e32 v119, v119, v30
	v_mul_f32_e32 v120, v120, v30
	v_mul_f32_e32 v121, v121, v30
	v_mul_f32_e32 v122, v122, v30
	v_mul_f32_e32 v123, v123, v30
	v_mul_f32_e32 v124, v124, v30
	v_mul_f32_e32 v125, v125, v30
	v_mul_f32_e32 v126, v126, v30
	v_mul_f32_e32 v127, v127, v30
	v_cvt_pk_fp8_f32 v112, v112, v113
	v_cvt_pk_fp8_f32 v116, v116, v117
	v_cvt_pk_fp8_f32 v120, v120, v121
	v_cvt_pk_fp8_f32 v124, v124, v125
	v_cvt_pk_fp8_f32 v112, v114, v115 op_sel:[0,0,1]
	v_cvt_pk_fp8_f32 v116, v118, v119 op_sel:[0,0,1]
	v_cvt_pk_fp8_f32 v120, v122, v123 op_sel:[0,0,1]
	v_cvt_pk_fp8_f32 v124, v126, v127 op_sel:[0,0,1]
	global_store_dword v[10:11], v112, off
	global_store_dword v[10:11], v116, off offset:256
	global_store_dword v[10:11], v120, off offset:512
	global_store_dword v[10:11], v124, off offset:768
	v_lshl_add_u64 v[10:11], v[10:11], 0, s[100:101]
	v_cmp_lt_f32_e64 s[12:13], 0, v6
	v_div_scale_f32 v24, s[4:5], s64, s64, v6
	v_rcp_f32_e32 v25, v24
	v_div_scale_f32 v26, vcc, v6, s64, v6
	v_fma_f32 v27, -v24, v25, 1.0
	v_fmac_f32_e32 v25, v27, v25
	v_mul_f32_e32 v27, v26, v25
	v_fma_f32 v28, -v24, v27, v26
	v_fmac_f32_e32 v27, v28, v25
	v_fma_f32 v24, -v24, v27, v26
	v_div_fmas_f32 v24, v24, v25, v27
	v_div_fixup_f32 v29, v24, s64, v6
	v_cndmask_b32_e64 v29, 1.0, v29, s[12:13]
	v_add_u32_e32 v15, 0xc000, v14
	s_and_saveexec_b64 s[56:57], s[10:11]
	global_store_dword v15, v29, s[16:17]
	s_or_b64 exec, exec, s[56:57]
	v_div_scale_f32 v24, s[4:5], v6, v6, s64
	v_rcp_f32_e32 v25, v24
	v_div_scale_f32 v26, vcc, s64, v6, s64
	v_fma_f32 v27, -v24, v25, 1.0
	v_fmac_f32_e32 v25, v27, v25
	v_mul_f32_e32 v27, v26, v25
	v_fma_f32 v28, -v24, v27, v26
	v_fmac_f32_e32 v27, v28, v25
	v_fma_f32 v24, -v24, v27, v26
	v_div_fmas_f32 v24, v24, v25, v27
	v_div_fixup_f32 v30, v24, v6, s64
	v_cndmask_b32_e64 v30, 1.0, v30, s[12:13]
	v_mul_f32_e32 v172, v172, v30
	v_mul_f32_e32 v173, v173, v30
	v_mul_f32_e32 v174, v174, v30
	v_mul_f32_e32 v175, v175, v30
	v_mul_f32_e32 v176, v176, v30
	v_mul_f32_e32 v177, v177, v30
	v_mul_f32_e32 v178, v178, v30
	v_mul_f32_e32 v179, v179, v30
	v_mul_f32_e32 v180, v180, v30
	v_mul_f32_e32 v181, v181, v30
	v_mul_f32_e32 v182, v182, v30
	v_mul_f32_e32 v183, v183, v30
	v_mul_f32_e32 v184, v184, v30
	v_mul_f32_e32 v185, v185, v30
	v_mul_f32_e32 v186, v186, v30
	v_mul_f32_e32 v187, v187, v30
	v_cvt_pk_fp8_f32 v172, v172, v173
	v_cvt_pk_fp8_f32 v176, v176, v177
	v_cvt_pk_fp8_f32 v180, v180, v181
	v_cvt_pk_fp8_f32 v184, v184, v185
	v_cvt_pk_fp8_f32 v172, v174, v175 op_sel:[0,0,1]
	v_cvt_pk_fp8_f32 v176, v178, v179 op_sel:[0,0,1]
	v_cvt_pk_fp8_f32 v180, v182, v183 op_sel:[0,0,1]
	v_cvt_pk_fp8_f32 v184, v186, v187 op_sel:[0,0,1]
	global_store_dword v[10:11], v172, off
	global_store_dword v[10:11], v176, off offset:256
	global_store_dword v[10:11], v180, off offset:512
	global_store_dword v[10:11], v184, off offset:768
	v_lshl_add_u64 v[10:11], v[10:11], 0, s[100:101]
	v_cmp_lt_f32_e64 s[12:13], 0, v7
	v_div_scale_f32 v24, s[4:5], s64, s64, v7
	v_rcp_f32_e32 v25, v24
	v_div_scale_f32 v26, vcc, v7, s64, v7
	v_fma_f32 v27, -v24, v25, 1.0
	v_fmac_f32_e32 v25, v27, v25
	v_mul_f32_e32 v27, v26, v25
	v_fma_f32 v28, -v24, v27, v26
	v_fmac_f32_e32 v27, v28, v25
	v_fma_f32 v24, -v24, v27, v26
	v_div_fmas_f32 v24, v24, v25, v27
	v_div_fixup_f32 v29, v24, s64, v7
	v_cndmask_b32_e64 v29, 1.0, v29, s[12:13]
	v_add_u32_e32 v15, 0xe000, v14
	s_and_saveexec_b64 s[56:57], s[10:11]
	global_store_dword v15, v29, s[16:17]
	s_or_b64 exec, exec, s[56:57]
	v_div_scale_f32 v24, s[4:5], v7, v7, s64
	v_rcp_f32_e32 v25, v24
	v_div_scale_f32 v26, vcc, s64, v7, s64
	v_fma_f32 v27, -v24, v25, 1.0
	v_fmac_f32_e32 v25, v27, v25
	v_mul_f32_e32 v27, v26, v25
	v_fma_f32 v28, -v24, v27, v26
	v_fmac_f32_e32 v27, v28, v25
	v_fma_f32 v24, -v24, v27, v26
	v_div_fmas_f32 v24, v24, v25, v27
	v_div_fixup_f32 v30, v24, v7, s64
	v_cndmask_b32_e64 v30, 1.0, v30, s[12:13]
	v_mul_f32_e32 v188, v188, v30
	v_mul_f32_e32 v189, v189, v30
	v_mul_f32_e32 v190, v190, v30
	v_mul_f32_e32 v191, v191, v30
	v_mul_f32_e32 v192, v192, v30
	v_mul_f32_e32 v193, v193, v30
	v_mul_f32_e32 v194, v194, v30
	v_mul_f32_e32 v195, v195, v30
	v_mul_f32_e32 v196, v196, v30
	v_mul_f32_e32 v197, v197, v30
	v_mul_f32_e32 v198, v198, v30
	v_mul_f32_e32 v199, v199, v30
	v_mul_f32_e32 v200, v200, v30
	v_mul_f32_e32 v201, v201, v30
	v_mul_f32_e32 v202, v202, v30
	v_mul_f32_e32 v203, v203, v30
	v_cvt_pk_fp8_f32 v188, v188, v189
	v_cvt_pk_fp8_f32 v192, v192, v193
	v_cvt_pk_fp8_f32 v196, v196, v197
	v_cvt_pk_fp8_f32 v200, v200, v201
	v_cvt_pk_fp8_f32 v188, v190, v191 op_sel:[0,0,1]
	v_cvt_pk_fp8_f32 v192, v194, v195 op_sel:[0,0,1]
	v_cvt_pk_fp8_f32 v196, v198, v199 op_sel:[0,0,1]
	v_cvt_pk_fp8_f32 v200, v202, v203 op_sel:[0,0,1]
	global_store_dword v[10:11], v188, off
	global_store_dword v[10:11], v192, off offset:256
	global_store_dword v[10:11], v196, off offset:512
	global_store_dword v[10:11], v200, off offset:768
	s_branch .LBB0_605
.Lmy_fp8o_1:
	v_cmp_lt_i32_e32 vcc, v223, v218
	s_mov_b64 s[28:29], 0
	v_mov_b32_e32 v16, v226
	v_cndmask_b32_e32 v0, v161, v223, vcc
	v_cmp_lt_i32_e32 vcc, v224, v218
	v_lshlrev_b32_e32 v18, 2, v0
	s_nop 0
	v_cndmask_b32_e32 v0, v161, v224, vcc
	v_cmp_lt_i32_e32 vcc, v222, v218
	v_lshlrev_b32_e32 v19, 2, v0
	s_nop 0
	v_cndmask_b32_e32 v0, v161, v222, vcc
	v_cmp_lt_i32_e32 vcc, v221, v218
	v_lshlrev_b32_e32 v20, 2, v0
	s_nop 0
	v_cndmask_b32_e32 v0, v161, v221, vcc
	v_cmp_lt_i32_e32 vcc, v220, v218
	v_lshlrev_b32_e32 v21, 2, v0
	s_nop 0
	v_cndmask_b32_e32 v0, v161, v220, vcc
	v_cmp_lt_i32_e32 vcc, v219, v218
	v_lshlrev_b32_e32 v22, 2, v0
	s_nop 0
	v_cndmask_b32_e32 v0, v161, v219, vcc
	v_lshlrev_b32_e32 v23, 2, v0
	s_branch .LBB0_598
